# nt policy also on the residual-epilogue read-once xold loads and the final-norm XB load
# baseline (speedup 1.0000x reference)
; __device__ __forceinline__ unsigned cvt_pk_bf16(float lo, float hi) { unsigned r; asm volatile("v_cvt_pk_bf16_f32 %0, %1, %2" : "=v"(r) : "v"(lo), "v"(hi)); return r; }
; __device__ __forceinline__ float bflo(unsigned w) { return __uint_as_float(w << 16); }
; __device__ __forceinline__ float bfhi(unsigned w) { return __uint_as_float(w & 0xffff0000u); }
; template <bool RD32>
; __device__ __forceinline__ void res_rows(const float* __restrict__ xold32, const bf16_t* __restrict__ xoldb, bf16_t* __restrict__ xb, float* __restrict__ ssq, const f32x4 (&acc)[2][2][4][2], int row0, int col0, int slot) {
;     f32x4 xo[2][2][2];
;     float ssv[8];
;     auto ld = [&](size_t o, f32x4& a, f32x4& b) { if (RD32) { a = *(const f32x4*)(xold32 + o); b = *(const f32x4*)(xold32 + o + 4); }
;         else { const u32x4 w = *(const u32x4*)(xoldb + o); a = (f32x4){bflo(w.x), bfhi(w.x), bflo(w.y), bfhi(w.y)}; b = (f32x4){bflo(w.z), bfhi(w.z), bflo(w.w), bfhi(w.w)}; } };
; #pragma unroll
;     for (int bj = 0; bj < 2; ++bj) ld((size_t)row0 * D + col0 + bj * HALF, xo[0][bj][0], xo[0][bj][1]);
; #pragma unroll
;     for (int idx = 0; idx < 8; ++idx) {
;         const int ai = idx >> 2, m = idx & 3; const int r = row0 + ai * HALF + m * 16; const size_t off = (size_t)r * D + col0;
;         if (idx < 7) { const int ai2 = (idx + 1) >> 2, m2 = (idx + 1) & 3; const size_t off2 = (size_t)(row0 + ai2 * HALF + m2 * 16) * D + col0;
; #pragma unroll
;             for (int bj = 0; bj < 2; ++bj) ld(off2 + bj * HALF, xo[(idx + 1) & 1][bj][0], xo[(idx + 1) & 1][bj][1]); }
;         float ss = 0.f;
; #pragma unroll
;         for (int bj = 0; bj < 2; ++bj) { const f32x4 x0 = xo[idx & 1][bj][0] + acc[ai][bj][m][0], x1 = xo[idx & 1][bj][1] + acc[ai][bj][m][1];
;             u32x4 w; w.x = cvt_pk_bf16(x0[0], x0[1]); w.y = cvt_pk_bf16(x0[2], x0[3]); w.z = cvt_pk_bf16(x1[0], x1[1]); w.w = cvt_pk_bf16(x1[2], x1[3]);
;             *(u32x4*)(xb + off + bj * HALF) = w;
;             ss += ((x0[0] * x0[0] + x0[1] * x0[1]) + (x0[2] * x0[2] + x0[3] * x0[3])) + ((x1[0] * x1[0] + x1[1] * x1[1]) + (x1[2] * x1[2] + x1[3] * x1[3])); }
;         ss += __shfl_xor(ss, 16); ss += __shfl_xor(ss, 32);
;         ssv[idx] = ss;
;     }
.LBB0_421:
	v_lshl_add_u32 v166, s5, 8, v217
	v_lshl_or_b32 v132, s4, 8, v219
	v_lshl_or_b32 v222, s4, 2, v220
	v_ashrrev_i32_e32 v167, 31, v166
	v_or_b32_e32 v223, s95, v222
	v_ashrrev_i32_e32 v133, 31, v132
	s_andn2_b64 vcc, exec, s[48:49]
	v_lshlrev_b64 v[174:175], 11, v[166:167]
	v_or_b32_e32 v172, 16, v166
	v_or_b32_e32 v170, 32, v166
	v_or_b32_e32 v168, 48, v166
	s_cbranch_vccnz .LBB0_436
	v_lshl_add_u64 v[128:129], s[58:59], 0, v[174:175]
	v_lshlrev_b64 v[134:135], 1, v[132:133]
	v_lshl_add_u64 v[136:137], v[128:129], 0, v[134:135]
	global_load_dwordx4 v[128:131], v[136:137], off nt
	v_ashrrev_i32_e32 v173, 31, v172
	v_ashrrev_i32_e32 v171, 31, v170
	s_mov_b64 s[4:5], 0x40000
	s_waitcnt vmcnt(0)
	v_lshlrev_b32_e32 v138, 16, v128
	v_and_b32_e32 v139, 0xffff0000, v128
	v_lshlrev_b32_e32 v140, 16, v129
	v_and_b32_e32 v141, 0xffff0000, v129
	v_lshlrev_b32_e32 v142, 16, v130
	v_and_b32_e32 v143, 0xffff0000, v130
	v_lshlrev_b32_e32 v176, 16, v131
	v_and_b32_e32 v177, 0xffff0000, v131
	global_load_dwordx4 v[128:131], v[136:137], off offset:256 nt
	v_pk_add_f32 v[140:141], v[126:127], v[140:141]
	v_pk_add_f32 v[138:139], v[124:125], v[138:139]
	v_pk_add_f32 v[176:177], v[122:123], v[176:177]
	v_pk_add_f32 v[142:143], v[120:121], v[142:143]
	s_waitcnt vmcnt(0)
	v_lshlrev_b32_e32 v178, 16, v128
	v_and_b32_e32 v179, 0xffff0000, v128
	v_lshlrev_b32_e32 v180, 16, v129
	v_and_b32_e32 v181, 0xffff0000, v129
	v_lshlrev_b32_e32 v182, 16, v130
	v_and_b32_e32 v183, 0xffff0000, v130
	v_lshlrev_b32_e32 v202, 16, v131
	v_and_b32_e32 v203, 0xffff0000, v131
	v_lshl_add_u64 v[130:131], s[58:59], 0, v[134:135]
	v_lshlrev_b64 v[128:129], 11, v[172:173]
	v_lshl_add_u64 v[184:185], v[130:131], 0, v[128:129]
	global_load_dwordx4 v[134:137], v[184:185], off nt
	v_lshl_add_u64 v[128:129], v[130:131], 0, v[174:175]
	s_waitcnt vmcnt(0)
	v_lshlrev_b32_e32 v186, 16, v134
	v_and_b32_e32 v187, 0xffff0000, v134
	v_lshlrev_b32_e32 v190, 16, v135
	v_and_b32_e32 v191, 0xffff0000, v135
	v_lshlrev_b32_e32 v188, 16, v136
	v_and_b32_e32 v189, 0xffff0000, v136
	v_lshlrev_b32_e32 v192, 16, v137
	v_and_b32_e32 v193, 0xffff0000, v137
	global_load_dwordx4 v[134:137], v[184:185], off offset:256 nt
	v_pk_add_f32 v[190:191], v[110:111], v[190:191]
	v_pk_add_f32 v[192:193], v[106:107], v[192:193]
	s_waitcnt vmcnt(0)
	v_lshlrev_b32_e32 v194, 16, v134
	v_and_b32_e32 v195, 0xffff0000, v134
	v_lshlrev_b32_e32 v198, 16, v135
	v_and_b32_e32 v199, 0xffff0000, v135
	v_cvt_pk_bf16_f32 v134, v138, v139
	v_cvt_pk_bf16_f32 v135, v140, v141
	v_lshlrev_b32_e32 v196, 16, v136
	v_and_b32_e32 v197, 0xffff0000, v136
	v_lshlrev_b32_e32 v200, 16, v137
	v_and_b32_e32 v201, 0xffff0000, v137
	v_cvt_pk_bf16_f32 v136, v142, v143
	v_cvt_pk_bf16_f32 v137, v176, v177
	global_store_dwordx4 v[128:129], v[134:137], off nt
	v_pk_add_f32 v[196:197], v[96:97], v[196:197]
	s_nop 0
	v_mul_f32_e32 v134, v139, v139
	v_mul_f32_e32 v135, v141, v141
	v_fmac_f32_e32 v134, v138, v138
	v_fmac_f32_e32 v135, v140, v140
	v_add_f32_e32 v134, v134, v135
	v_mul_f32_e32 v135, v143, v143
	v_mul_f32_e32 v136, v177, v177
	v_fmac_f32_e32 v135, v142, v142
	v_fmac_f32_e32 v136, v176, v176
	v_add_f32_e32 v135, v135, v136
	v_add_f32_e32 v152, v134, v135
	v_pk_add_f32 v[138:139], v[118:119], v[180:181]
	v_pk_add_f32 v[140:141], v[116:117], v[178:179]
	v_pk_add_f32 v[142:143], v[114:115], v[202:203]
	v_cvt_pk_bf16_f32 v134, v140, v141
	v_cvt_pk_bf16_f32 v135, v138, v139
	v_pk_add_f32 v[176:177], v[112:113], v[182:183]
	s_nop 0
	v_cvt_pk_bf16_f32 v136, v176, v177
	v_cvt_pk_bf16_f32 v137, v142, v143
	global_store_dwordx4 v[128:129], v[134:137], off offset:256 nt
	s_nop 1
	v_mul_f32_e32 v134, v141, v141
	v_mul_f32_e32 v135, v139, v139
	v_fmac_f32_e32 v134, v140, v140
	v_fmac_f32_e32 v135, v138, v138
	v_add_f32_e32 v134, v134, v135
	v_mul_f32_e32 v135, v177, v177
	v_mul_f32_e32 v136, v143, v143
	v_fmac_f32_e32 v135, v176, v176
	v_fmac_f32_e32 v136, v142, v142
	v_add_f32_e32 v135, v135, v136
	v_and_b32_e32 v136, 64, v209
	v_add_f32_e32 v134, v134, v135
	v_xor_b32_e32 v135, 16, v209
	v_add_u32_e32 v136, 64, v136
	v_cmp_lt_i32_e32 vcc, v135, v136
	v_add_f32_e32 v134, v152, v134
	s_nop 0
	v_cndmask_b32_e32 v135, v209, v135, vcc
	v_lshlrev_b32_e32 v152, 2, v135
	ds_bpermute_b32 v135, v152, v134
	s_waitcnt lgkmcnt(0)
	v_add_f32_e32 v173, v134, v135
	v_xor_b32_e32 v134, 32, v209
	v_cmp_lt_i32_e32 vcc, v134, v136
	s_nop 1
	v_cndmask_b32_e32 v134, v209, v134, vcc
	v_lshlrev_b32_e32 v225, 2, v134
	v_lshlrev_b64 v[134:135], 11, v[170:171]
	v_lshl_add_u64 v[134:135], v[130:131], 0, v[134:135]
	global_load_dwordx4 v[136:139], v[134:135], off nt
	global_load_dwordx4 v[202:205], v[134:135], off offset:256 nt
	v_mul_f32_e32 v171, v191, v191
	v_fmac_f32_e32 v171, v190, v190
	ds_bpermute_b32 v224, v225, v173
	s_waitcnt vmcnt(1)
	v_lshlrev_b32_e32 v176, 16, v138
	v_and_b32_e32 v177, 0xffff0000, v138
	v_lshlrev_b32_e32 v180, 16, v139
	v_and_b32_e32 v181, 0xffff0000, v139
	s_waitcnt vmcnt(0)
; __device__ __forceinline__ unsigned cvt_pk_bf16(float lo, float hi) { unsigned r; asm volatile("v_cvt_pk_bf16_f32 %0, %1, %2" : "=v"(r) : "v"(lo), "v"(hi)); return r; }
; template <bool RD32>
; __device__ __forceinline__ void res_rows(const float* __restrict__ xold32, const bf16_t* __restrict__ xoldb, bf16_t* __restrict__ xb, float* __restrict__ ssq, const f32x4 (&acc)[2][2][4][2], int row0, int col0, int slot) {
;     ...
;     for (int idx = 0; idx < 8; ++idx) {
;         const int ai = idx >> 2, m = idx & 3; const int r = row0 + ai * HALF + m * 16; const size_t off = (size_t)r * D + col0;
;         if (idx < 7) { const int ai2 = (idx + 1) >> 2, m2 = (idx + 1) & 3; const size_t off2 = (size_t)(row0 + ai2 * HALF + m2 * 16) * D + col0;
; #pragma unroll
;             for (int bj = 0; bj < 2; ++bj) ld(off2 + bj * HALF, xo[(idx + 1) & 1][bj][0], xo[(idx + 1) & 1][bj][1]); }
;         float ss = 0.f;
; #pragma unroll
;         for (int bj = 0; bj < 2; ++bj) { const f32x4 x0 = xo[idx & 1][bj][0] + acc[ai][bj][m][0], x1 = xo[idx & 1][bj][1] + acc[ai][bj][m][1];
;             u32x4 w; w.x = cvt_pk_bf16(x0[0], x0[1]); w.y = cvt_pk_bf16(x0[2], x0[3]); w.z = cvt_pk_bf16(x1[0], x1[1]); w.w = cvt_pk_bf16(x1[2], x1[3]);
;             *(u32x4*)(xb + off + bj * HALF) = w;
;             ss += ((x0[0] * x0[0] + x0[1] * x0[1]) + (x0[2] * x0[2] + x0[3] * x0[3])) + ((x1[0] * x1[0] + x1[1] * x1[1]) + (x1[2] * x1[2] + x1[3] * x1[3])); }
;         ss += __shfl_xor(ss, 16); ss += __shfl_xor(ss, 32);
;         ssv[idx] = ss;
;     }
	v_lshlrev_b32_e32 v138, 16, v202
	v_and_b32_e32 v139, 0xffff0000, v202
	v_lshlrev_b32_e32 v142, 16, v203
	v_and_b32_e32 v143, 0xffff0000, v203
	v_pk_add_f32 v[202:203], v[108:109], v[186:187]
	v_lshlrev_b32_e32 v178, 16, v136
	v_mul_f32_e32 v169, v203, v203
	v_and_b32_e32 v179, 0xffff0000, v136
	v_lshlrev_b32_e32 v182, 16, v137
	v_and_b32_e32 v183, 0xffff0000, v137
	v_lshlrev_b32_e32 v136, 16, v204
	v_and_b32_e32 v137, 0xffff0000, v204
	v_lshlrev_b32_e32 v140, 16, v205
	v_and_b32_e32 v141, 0xffff0000, v205
	v_pk_add_f32 v[204:205], v[104:105], v[188:189]
	v_cvt_pk_bf16_f32 v186, v202, v203
	v_fmac_f32_e32 v169, v202, v202
	v_cvt_pk_bf16_f32 v187, v190, v191
	v_cvt_pk_bf16_f32 v188, v204, v205
	v_cvt_pk_bf16_f32 v189, v192, v193
	global_store_dwordx4 v[184:185], v[186:189], off nt
	v_add_f32_e32 v169, v169, v171
	v_mul_f32_e32 v171, v205, v205
	v_mul_f32_e32 v186, v193, v193
	v_fmac_f32_e32 v171, v204, v204
	v_fmac_f32_e32 v186, v192, v192
	v_add_f32_e32 v171, v171, v186
	v_pk_add_f32 v[190:191], v[102:103], v[198:199]
	v_pk_add_f32 v[192:193], v[100:101], v[194:195]
	v_add_f32_e32 v169, v169, v171
	v_pk_add_f32 v[194:195], v[98:99], v[200:201]
	v_cvt_pk_bf16_f32 v186, v192, v193
	v_cvt_pk_bf16_f32 v187, v190, v191
	v_cvt_pk_bf16_f32 v188, v196, v197
	v_mul_f32_e32 v171, v193, v193
	v_cvt_pk_bf16_f32 v189, v194, v195
	global_store_dwordx4 v[184:185], v[186:189], off offset:256 nt
	v_mul_f32_e32 v184, v191, v191
	v_fmac_f32_e32 v171, v192, v192
	v_fmac_f32_e32 v184, v190, v190
	v_add_f32_e32 v171, v171, v184
	v_mul_f32_e32 v184, v197, v197
	v_mul_f32_e32 v185, v195, v195
	v_fmac_f32_e32 v184, v196, v196
	v_fmac_f32_e32 v185, v194, v194
	v_add_f32_e32 v184, v184, v185
	v_add_f32_e32 v171, v171, v184
	v_add_f32_e32 v169, v169, v171
	ds_bpermute_b32 v171, v152, v169
	v_pk_add_f32 v[182:183], v[94:95], v[182:183]
	v_pk_add_f32 v[194:195], v[92:93], v[178:179]
	v_pk_add_f32 v[180:181], v[90:91], v[180:181]
	v_pk_add_f32 v[142:143], v[86:87], v[142:143]
	s_waitcnt lgkmcnt(0)
	v_add_f32_e32 v171, v169, v171
	v_ashrrev_i32_e32 v169, 31, v168
	v_lshlrev_b64 v[184:185], 11, v[168:169]
	v_lshl_add_u64 v[130:131], v[130:131], 0, v[184:185]
	global_load_dwordx4 v[184:187], v[130:131], off nt
	global_load_dwordx4 v[202:205], v[130:131], off offset:256 nt
	v_mul_f32_e32 v169, v195, v195
	v_fmac_f32_e32 v169, v194, v194
	v_pk_add_f32 v[140:141], v[82:83], v[140:141]
	ds_bpermute_b32 v226, v225, v171
	s_waitcnt vmcnt(1)
	v_lshlrev_b32_e32 v192, 16, v186
	v_and_b32_e32 v193, 0xffff0000, v186
	v_lshlrev_b32_e32 v198, 16, v187
	v_and_b32_e32 v199, 0xffff0000, v187
	s_waitcnt vmcnt(0)
	v_lshlrev_b32_e32 v186, 16, v202
	v_and_b32_e32 v187, 0xffff0000, v202
	v_lshlrev_b32_e32 v190, 16, v203
	v_and_b32_e32 v191, 0xffff0000, v203
	v_pk_add_f32 v[202:203], v[88:89], v[176:177]
	v_cvt_pk_bf16_f32 v176, v194, v195
	v_cvt_pk_bf16_f32 v177, v182, v183
	v_lshlrev_b32_e32 v196, 16, v184
	v_cvt_pk_bf16_f32 v178, v202, v203
	v_cvt_pk_bf16_f32 v179, v180, v181
	global_store_dwordx4 v[134:135], v[176:179], off nt
	v_and_b32_e32 v197, 0xffff0000, v184
	v_lshlrev_b32_e32 v200, 16, v185
	v_mul_f32_e32 v176, v183, v183
	v_fmac_f32_e32 v176, v182, v182
	v_add_f32_e32 v169, v169, v176
	v_mul_f32_e32 v176, v203, v203
	v_mul_f32_e32 v177, v181, v181
	v_fmac_f32_e32 v176, v202, v202
	v_fmac_f32_e32 v177, v180, v180
	v_add_f32_e32 v176, v176, v177
	v_add_f32_e32 v169, v169, v176
	v_pk_add_f32 v[176:177], v[84:85], v[138:139]
	v_pk_add_f32 v[178:179], v[80:81], v[136:137]
	v_cvt_pk_bf16_f32 v136, v176, v177
	v_cvt_pk_bf16_f32 v137, v142, v143
	v_and_b32_e32 v201, 0xffff0000, v185
	v_cvt_pk_bf16_f32 v138, v178, v179
	v_cvt_pk_bf16_f32 v139, v140, v141
	global_store_dwordx4 v[134:135], v[136:139], off offset:256 nt
	v_mul_f32_e32 v134, v177, v177
	v_mul_f32_e32 v135, v143, v143
	v_fmac_f32_e32 v134, v176, v176
	v_fmac_f32_e32 v135, v142, v142
	v_add_f32_e32 v134, v134, v135
	v_mul_f32_e32 v135, v179, v179
	v_mul_f32_e32 v136, v141, v141
	v_fmac_f32_e32 v135, v178, v178
	v_fmac_f32_e32 v136, v140, v140
	v_add_f32_e32 v135, v135, v136
	v_add_f32_e32 v134, v134, v135
	v_add_f32_e32 v134, v169, v134
	ds_bpermute_b32 v135, v152, v134
	v_lshlrev_b32_e32 v184, 16, v204
	v_and_b32_e32 v185, 0xffff0000, v204
	v_lshlrev_b32_e32 v188, 16, v205
	v_and_b32_e32 v189, 0xffff0000, v205
	s_waitcnt lgkmcnt(0)
	v_add_f32_e32 v169, v134, v135
	v_lshl_add_u64 v[134:135], v[128:129], 0, s[4:5]
	s_mov_b32 s4, 0x40000
	v_add_co_u32_e32 v136, vcc, s4, v128
	global_load_dwordx4 v[202:205], v[134:135], off offset:256 nt
	s_nop 0
	v_addc_co_u32_e32 v137, vcc, 0, v129, vcc
	global_load_dwordx4 v[138:141], v[136:137], off nt
	v_pk_add_f32 v[192:193], v[72:73], v[192:193]
	v_pk_add_f32 v[200:201], v[78:79], v[200:201]
	v_pk_add_f32 v[190:191], v[70:71], v[190:191]
	v_pk_add_f32 v[188:189], v[66:67], v[188:189]
	s_mov_b64 s[4:5], 0x48000
	ds_bpermute_b32 v227, v225, v169
	s_waitcnt vmcnt(1)
	v_lshlrev_b32_e32 v176, 16, v203
	v_and_b32_e32 v177, 0xffff0000, v203
	v_lshlrev_b32_e32 v142, 16, v205
	s_waitcnt vmcnt(0)
; __device__ __forceinline__ unsigned cvt_pk_bf16(float lo, float hi) { unsigned r; asm volatile("v_cvt_pk_bf16_f32 %0, %1, %2" : "=v"(r) : "v"(lo), "v"(hi)); return r; }
; template <bool RD32>
; __device__ __forceinline__ void res_rows(const float* __restrict__ xold32, const bf16_t* __restrict__ xoldb, bf16_t* __restrict__ xb, float* __restrict__ ssq, const f32x4 (&acc)[2][2][4][2], int row0, int col0, int slot) {
;     ...
;     for (int idx = 0; idx < 8; ++idx) {
;         const int ai = idx >> 2, m = idx & 3; const int r = row0 + ai * HALF + m * 16; const size_t off = (size_t)r * D + col0;
;         if (idx < 7) { const int ai2 = (idx + 1) >> 2, m2 = (idx + 1) & 3; const size_t off2 = (size_t)(row0 + ai2 * HALF + m2 * 16) * D + col0;
; #pragma unroll
;             for (int bj = 0; bj < 2; ++bj) ld(off2 + bj * HALF, xo[(idx + 1) & 1][bj][0], xo[(idx + 1) & 1][bj][1]); }
;         float ss = 0.f;
; #pragma unroll
;         for (int bj = 0; bj < 2; ++bj) { const f32x4 x0 = xo[idx & 1][bj][0] + acc[ai][bj][m][0], x1 = xo[idx & 1][bj][1] + acc[ai][bj][m][1];
;             u32x4 w; w.x = cvt_pk_bf16(x0[0], x0[1]); w.y = cvt_pk_bf16(x0[2], x0[3]); w.z = cvt_pk_bf16(x1[0], x1[1]); w.w = cvt_pk_bf16(x1[2], x1[3]);
;             *(u32x4*)(xb + off + bj * HALF) = w;
;             ss += ((x0[0] * x0[0] + x0[1] * x0[1]) + (x0[2] * x0[2] + x0[3] * x0[3])) + ((x1[0] * x1[0] + x1[1] * x1[1]) + (x1[2] * x1[2] + x1[3] * x1[3])); }
;         ss += __shfl_xor(ss, 16); ss += __shfl_xor(ss, 32);
;         ssv[idx] = ss;
;     }
	v_lshlrev_b32_e32 v180, 16, v138
	v_and_b32_e32 v181, 0xffff0000, v138
	v_lshlrev_b32_e32 v194, 16, v139
	v_and_b32_e32 v195, 0xffff0000, v139
	v_lshlrev_b32_e32 v178, 16, v140
	v_and_b32_e32 v179, 0xffff0000, v140
	v_lshlrev_b32_e32 v182, 16, v141
	v_and_b32_e32 v183, 0xffff0000, v141
	v_lshlrev_b32_e32 v140, 16, v202
	v_and_b32_e32 v141, 0xffff0000, v202
	v_lshlrev_b32_e32 v138, 16, v204
	v_and_b32_e32 v139, 0xffff0000, v204
	v_and_b32_e32 v143, 0xffff0000, v205
	v_pk_add_f32 v[202:203], v[76:77], v[196:197]
	v_pk_add_f32 v[204:205], v[74:75], v[198:199]
	v_cvt_pk_bf16_f32 v196, v202, v203
	v_cvt_pk_bf16_f32 v197, v200, v201
	v_cvt_pk_bf16_f32 v198, v192, v193
	v_mul_f32_e32 v193, v193, v193
	v_cvt_pk_bf16_f32 v199, v204, v205
	global_store_dwordx4 v[130:131], v[196:199], off nt
	v_fmac_f32_e32 v193, v192, v192
	v_mul_f32_e32 v192, v205, v205
	v_mul_f32_e32 v196, v203, v203
	v_mul_f32_e32 v197, v201, v201
	v_fmac_f32_e32 v196, v202, v202
	v_fmac_f32_e32 v197, v200, v200
	v_fmac_f32_e32 v192, v204, v204
	v_add_f32_e32 v196, v196, v197
	v_add_f32_e32 v192, v193, v192
	v_add_f32_e32 v198, v196, v192
	v_pk_add_f32 v[192:193], v[68:69], v[186:187]
	v_pk_add_f32 v[196:197], v[64:65], v[184:185]
	v_cvt_pk_bf16_f32 v184, v192, v193
	v_cvt_pk_bf16_f32 v185, v190, v191
	v_pk_add_f32 v[182:183], v[58:59], v[182:183]
	v_cvt_pk_bf16_f32 v186, v196, v197
	v_cvt_pk_bf16_f32 v187, v188, v189
	global_store_dwordx4 v[130:131], v[184:187], off offset:256 nt
	v_mul_f32_e32 v130, v193, v193
	v_mul_f32_e32 v131, v191, v191
	v_fmac_f32_e32 v130, v192, v192
	v_fmac_f32_e32 v131, v190, v190
	v_add_f32_e32 v130, v130, v131
	v_mul_f32_e32 v131, v197, v197
	v_mul_f32_e32 v184, v189, v189
	v_fmac_f32_e32 v131, v196, v196
	v_fmac_f32_e32 v184, v188, v188
	v_add_f32_e32 v131, v131, v184
	v_add_f32_e32 v130, v130, v131
	v_add_f32_e32 v130, v198, v130
	ds_bpermute_b32 v131, v152, v130
	v_pk_add_f32 v[184:185], v[62:63], v[194:195]
	v_pk_add_f32 v[194:195], v[60:61], v[180:181]
	v_pk_add_f32 v[176:177], v[54:55], v[176:177]
	v_pk_add_f32 v[140:141], v[52:53], v[140:141]
	s_waitcnt lgkmcnt(0)
	v_add_f32_e32 v228, v130, v131
	v_lshl_add_u64 v[130:131], v[128:129], 0, s[4:5]
	s_mov_b32 s4, 0x48000
	v_add_co_u32_e32 v186, vcc, s4, v128
	global_load_dwordx4 v[230:233], v[130:131], off offset:256 nt
	s_nop 0
	v_addc_co_u32_e32 v187, vcc, 0, v129, vcc
	global_load_dwordx4 v[188:191], v[186:187], off nt
	v_pk_add_f32 v[142:143], v[50:51], v[142:143]
	s_mov_b64 s[4:5], 0x50000
	ds_bpermute_b32 v229, v225, v228
	s_waitcnt vmcnt(1)
	v_lshlrev_b32_e32 v196, 16, v231
	v_and_b32_e32 v197, 0xffff0000, v231
	v_lshlrev_b32_e32 v192, 16, v233
	s_waitcnt vmcnt(0)
	v_lshlrev_b32_e32 v198, 16, v190
	v_and_b32_e32 v199, 0xffff0000, v190
	v_lshlrev_b32_e32 v202, 16, v191
	v_and_b32_e32 v203, 0xffff0000, v191
	v_lshlrev_b32_e32 v190, 16, v230
	v_and_b32_e32 v191, 0xffff0000, v230
	v_pk_add_f32 v[230:231], v[56:57], v[178:179]
	v_cvt_pk_bf16_f32 v178, v194, v195
	v_cvt_pk_bf16_f32 v179, v184, v185
	v_lshlrev_b32_e32 v200, 16, v188
	v_cvt_pk_bf16_f32 v180, v230, v231
	v_cvt_pk_bf16_f32 v181, v182, v183
	global_store_dwordx4 v[136:137], v[178:181], off nt
	v_mul_f32_e32 v136, v195, v195
	v_mul_f32_e32 v137, v185, v185
	v_fmac_f32_e32 v136, v194, v194
	v_fmac_f32_e32 v137, v184, v184
	v_add_f32_e32 v136, v136, v137
	v_mul_f32_e32 v137, v231, v231
	v_mul_f32_e32 v178, v183, v183
	v_fmac_f32_e32 v137, v230, v230
	v_fmac_f32_e32 v178, v182, v182
	v_add_f32_e32 v137, v137, v178
	v_add_f32_e32 v180, v136, v137
	v_pk_add_f32 v[178:179], v[48:49], v[138:139]
	v_cvt_pk_bf16_f32 v136, v140, v141
	v_cvt_pk_bf16_f32 v137, v176, v177
	v_and_b32_e32 v201, 0xffff0000, v188
	v_cvt_pk_bf16_f32 v138, v178, v179
	v_cvt_pk_bf16_f32 v139, v142, v143
	global_store_dwordx4 v[134:135], v[136:139], off offset:256 nt
	v_mul_f32_e32 v134, v141, v141
	v_mul_f32_e32 v135, v177, v177
	v_fmac_f32_e32 v134, v140, v140
	v_fmac_f32_e32 v135, v176, v176
	v_add_f32_e32 v134, v134, v135
	v_mul_f32_e32 v135, v179, v179
	v_mul_f32_e32 v136, v143, v143
	v_fmac_f32_e32 v135, v178, v178
	v_fmac_f32_e32 v136, v142, v142
	v_add_f32_e32 v135, v135, v136
	v_add_f32_e32 v134, v134, v135
	v_add_f32_e32 v134, v180, v134
	ds_bpermute_b32 v135, v152, v134
	v_lshlrev_b32_e32 v204, 16, v189
	v_and_b32_e32 v205, 0xffff0000, v189
	v_lshlrev_b32_e32 v188, 16, v232
	v_and_b32_e32 v189, 0xffff0000, v232
	s_waitcnt lgkmcnt(0)
	v_add_f32_e32 v230, v134, v135
	v_lshl_add_u64 v[134:135], v[128:129], 0, s[4:5]
	s_mov_b32 s4, 0x50000
	v_add_co_u32_e32 v136, vcc, s4, v128
	v_and_b32_e32 v193, 0xffff0000, v233
	s_nop 0
	v_addc_co_u32_e32 v137, vcc, 0, v129, vcc
	global_load_dwordx4 v[176:179], v[136:137], off nt
	global_load_dwordx4 v[232:235], v[134:135], off offset:256 nt
	v_pk_add_f32 v[194:195], v[46:47], v[204:205]
	v_pk_add_f32 v[204:205], v[44:45], v[200:201]
	v_pk_add_f32 v[202:203], v[42:43], v[202:203]
	v_pk_add_f32 v[190:191], v[36:37], v[190:191]
	v_pk_add_f32 v[192:193], v[34:35], v[192:193]
	s_mov_b64 s[4:5], 0x58000
	ds_bpermute_b32 v231, v225, v230
	s_waitcnt vmcnt(1)
	v_lshlrev_b32_e32 v140, 16, v176
	s_waitcnt vmcnt(0)
; __device__ __forceinline__ unsigned cvt_pk_bf16(float lo, float hi) { unsigned r; asm volatile("v_cvt_pk_bf16_f32 %0, %1, %2" : "=v"(r) : "v"(lo), "v"(hi)); return r; }
; template <bool RD32>
; __device__ __forceinline__ void res_rows(const float* __restrict__ xold32, const bf16_t* __restrict__ xoldb, bf16_t* __restrict__ xb, float* __restrict__ ssq, const f32x4 (&acc)[2][2][4][2], int row0, int col0, int slot) {
;     ...
;     for (int idx = 0; idx < 8; ++idx) {
;         const int ai = idx >> 2, m = idx & 3; const int r = row0 + ai * HALF + m * 16; const size_t off = (size_t)r * D + col0;
;         if (idx < 7) { const int ai2 = (idx + 1) >> 2, m2 = (idx + 1) & 3; const size_t off2 = (size_t)(row0 + ai2 * HALF + m2 * 16) * D + col0;
; #pragma unroll
;             for (int bj = 0; bj < 2; ++bj) ld(off2 + bj * HALF, xo[(idx + 1) & 1][bj][0], xo[(idx + 1) & 1][bj][1]); }
;         float ss = 0.f;
; #pragma unroll
;         for (int bj = 0; bj < 2; ++bj) { const f32x4 x0 = xo[idx & 1][bj][0] + acc[ai][bj][m][0], x1 = xo[idx & 1][bj][1] + acc[ai][bj][m][1];
;             u32x4 w; w.x = cvt_pk_bf16(x0[0], x0[1]); w.y = cvt_pk_bf16(x0[2], x0[3]); w.z = cvt_pk_bf16(x1[0], x1[1]); w.w = cvt_pk_bf16(x1[2], x1[3]);
;             *(u32x4*)(xb + off + bj * HALF) = w;
;             ss += ((x0[0] * x0[0] + x0[1] * x0[1]) + (x0[2] * x0[2] + x0[3] * x0[3])) + ((x1[0] * x1[0] + x1[1] * x1[1]) + (x1[2] * x1[2] + x1[3] * x1[3])); }
;         ss += __shfl_xor(ss, 16); ss += __shfl_xor(ss, 32);
;         ssv[idx] = ss;
;     }
;     const int fq = slot >> 6;
; #pragma unroll
;     for (int j = 0; j < 2; ++j) { const float v = fq == 0 ? ssv[j] : fq == 1 ? ssv[2 + j] : fq == 2 ? ssv[4 + j] : ssv[6 + j]; const int idx = 2 * fq + j;
;         ssq[(size_t)(row0 + (idx >> 2) * HALF + (idx & 3) * 16) * 16 + (slot & 15)] = v; }
	v_lshlrev_b32_e32 v180, 16, v232
	v_and_b32_e32 v181, 0xffff0000, v232
	v_lshlrev_b32_e32 v184, 16, v233
	v_and_b32_e32 v185, 0xffff0000, v233
	v_pk_add_f32 v[232:233], v[40:41], v[198:199]
	v_cvt_pk_bf16_f32 v198, v204, v205
	v_cvt_pk_bf16_f32 v199, v194, v195
	v_and_b32_e32 v141, 0xffff0000, v176
	v_cvt_pk_bf16_f32 v200, v232, v233
	v_cvt_pk_bf16_f32 v201, v202, v203
	global_store_dwordx4 v[186:187], v[198:201], off nt
	v_mul_f32_e32 v186, v205, v205
	v_mul_f32_e32 v187, v195, v195
	v_fmac_f32_e32 v186, v204, v204
	v_fmac_f32_e32 v187, v194, v194
	v_add_f32_e32 v186, v186, v187
	v_mul_f32_e32 v187, v233, v233
	v_mul_f32_e32 v194, v203, v203
	v_fmac_f32_e32 v187, v232, v232
	v_fmac_f32_e32 v194, v202, v202
	v_add_f32_e32 v187, v187, v194
	v_pk_add_f32 v[194:195], v[38:39], v[196:197]
	v_add_f32_e32 v198, v186, v187
	v_pk_add_f32 v[196:197], v[32:33], v[188:189]
	v_cvt_pk_bf16_f32 v186, v190, v191
	v_cvt_pk_bf16_f32 v187, v194, v195
	v_lshlrev_b32_e32 v176, 16, v177
	v_cvt_pk_bf16_f32 v188, v196, v197
	v_cvt_pk_bf16_f32 v189, v192, v193
	global_store_dwordx4 v[130:131], v[186:189], off offset:256 nt
	v_mul_f32_e32 v130, v191, v191
	v_mul_f32_e32 v131, v195, v195
	v_fmac_f32_e32 v130, v190, v190
	v_fmac_f32_e32 v131, v194, v194
	v_add_f32_e32 v130, v130, v131
	v_mul_f32_e32 v131, v197, v197
	v_mul_f32_e32 v186, v193, v193
	v_fmac_f32_e32 v131, v196, v196
	v_fmac_f32_e32 v186, v192, v192
	v_add_f32_e32 v131, v131, v186
	v_add_f32_e32 v130, v130, v131
	v_add_f32_e32 v130, v198, v130
	ds_bpermute_b32 v131, v152, v130
	v_lshl_add_u64 v[186:187], v[128:129], 0, s[4:5]
	s_mov_b32 s4, 0x58000
	v_add_co_u32_e32 v188, vcc, s4, v128
	s_waitcnt lgkmcnt(0)
	v_add_f32_e32 v198, v130, v131
	v_addc_co_u32_e32 v189, vcc, 0, v129, vcc
	global_load_dwordx4 v[128:131], v[188:189], off nt
	v_and_b32_e32 v177, 0xffff0000, v177
	v_lshlrev_b32_e32 v138, 16, v178
	v_and_b32_e32 v139, 0xffff0000, v178
	v_lshlrev_b32_e32 v142, 16, v179
	v_and_b32_e32 v143, 0xffff0000, v179
	v_pk_add_f32 v[176:177], v[30:31], v[176:177]
	v_pk_add_f32 v[140:141], v[28:29], v[140:141]
	v_pk_add_f32 v[142:143], v[26:27], v[142:143]
	v_pk_add_f32 v[138:139], v[24:25], v[138:139]
	v_lshlrev_b32_e32 v178, 16, v234
	v_and_b32_e32 v179, 0xffff0000, v234
	v_lshlrev_b32_e32 v182, 16, v235
	v_and_b32_e32 v183, 0xffff0000, v235
	ds_bpermute_b32 v199, v225, v198
	v_cmp_lt_u32_e32 vcc, 63, v222
	s_waitcnt vmcnt(0)
	v_lshlrev_b32_e32 v192, 16, v128
	v_and_b32_e32 v193, 0xffff0000, v128
	v_lshlrev_b32_e32 v196, 16, v129
	v_and_b32_e32 v197, 0xffff0000, v129
	v_lshlrev_b32_e32 v190, 16, v130
	v_and_b32_e32 v191, 0xffff0000, v130
	v_lshlrev_b32_e32 v194, 16, v131
	v_and_b32_e32 v195, 0xffff0000, v131
	global_load_dwordx4 v[128:131], v[186:187], off offset:256 nt
	s_waitcnt vmcnt(0)
	v_lshlrev_b32_e32 v200, 16, v128
	v_and_b32_e32 v201, 0xffff0000, v128
	v_lshlrev_b32_e32 v202, 16, v129
	v_and_b32_e32 v203, 0xffff0000, v129
	v_cvt_pk_bf16_f32 v128, v140, v141
	v_cvt_pk_bf16_f32 v129, v176, v177
	v_lshlrev_b32_e32 v204, 16, v130
	v_and_b32_e32 v205, 0xffff0000, v130
	v_lshlrev_b32_e32 v232, 16, v131
	v_and_b32_e32 v233, 0xffff0000, v131
	v_cvt_pk_bf16_f32 v130, v138, v139
	v_cvt_pk_bf16_f32 v131, v142, v143
	global_store_dwordx4 v[136:137], v[128:131], off nt
	v_pk_add_f32 v[136:137], v[22:23], v[184:185]
	s_nop 0
	v_mul_f32_e32 v128, v141, v141
	v_mul_f32_e32 v129, v177, v177
	v_fmac_f32_e32 v128, v140, v140
	v_fmac_f32_e32 v129, v176, v176
	v_add_f32_e32 v128, v128, v129
	v_mul_f32_e32 v129, v139, v139
	v_mul_f32_e32 v130, v143, v143
	v_fmac_f32_e32 v129, v138, v138
	v_fmac_f32_e32 v130, v142, v142
	v_add_f32_e32 v129, v129, v130
	v_add_f32_e32 v176, v128, v129
	v_pk_add_f32 v[138:139], v[20:21], v[180:181]
	v_pk_add_f32 v[140:141], v[18:19], v[182:183]
	v_cvt_pk_bf16_f32 v128, v138, v139
	v_cvt_pk_bf16_f32 v129, v136, v137
	v_pk_add_f32 v[142:143], v[16:17], v[178:179]
	s_nop 0
	v_cvt_pk_bf16_f32 v130, v142, v143
	v_cvt_pk_bf16_f32 v131, v140, v141
	global_store_dwordx4 v[134:135], v[128:131], off offset:256 nt
	s_nop 1
	v_mul_f32_e32 v128, v139, v139
	v_mul_f32_e32 v129, v137, v137
	v_fmac_f32_e32 v128, v138, v138
	v_fmac_f32_e32 v129, v136, v136
	v_add_f32_e32 v128, v128, v129
	v_mul_f32_e32 v129, v143, v143
	v_mul_f32_e32 v130, v141, v141
	v_fmac_f32_e32 v129, v142, v142
	v_fmac_f32_e32 v130, v140, v140
	v_add_f32_e32 v129, v129, v130
	v_add_f32_e32 v128, v128, v129
	v_add_f32_e32 v128, v176, v128
	ds_bpermute_b32 v129, v152, v128
	v_pk_add_f32 v[130:131], v[14:15], v[196:197]
	v_pk_add_f32 v[140:141], v[12:13], v[192:193]
	v_pk_add_f32 v[142:143], v[10:11], v[194:195]
	v_cvt_pk_bf16_f32 v136, v140, v141
	s_waitcnt lgkmcnt(0)
	v_add_f32_e32 v129, v128, v129
	v_cvt_pk_bf16_f32 v137, v130, v131
	v_mul_f32_e32 v128, v141, v141
	v_mul_f32_e32 v131, v131, v131
	v_pk_add_f32 v[176:177], v[8:9], v[190:191]
	v_fmac_f32_e32 v128, v140, v140
	v_fmac_f32_e32 v131, v130, v130
	v_add_f32_e32 v128, v128, v131
	v_mul_f32_e32 v130, v177, v177
	v_mul_f32_e32 v131, v143, v143
	v_fmac_f32_e32 v130, v176, v176
	v_fmac_f32_e32 v131, v142, v142
	v_add_f32_e32 v130, v130, v131
	v_add_f32_e32 v128, v128, v130
	v_pk_add_f32 v[130:131], v[6:7], v[202:203]
	v_pk_add_f32 v[140:141], v[4:5], v[200:201]
	v_cvt_pk_bf16_f32 v138, v176, v177
	v_cvt_pk_bf16_f32 v139, v142, v143
	global_store_dwordx4 v[188:189], v[136:139], off nt
	v_mul_f32_e32 v134, v141, v141
	v_pk_add_f32 v[142:143], v[2:3], v[232:233]
	v_cvt_pk_bf16_f32 v136, v140, v141
	v_cvt_pk_bf16_f32 v137, v130, v131
	v_mul_f32_e32 v131, v131, v131
	v_pk_add_f32 v[176:177], v[0:1], v[204:205]
	v_fmac_f32_e32 v134, v140, v140
	v_fmac_f32_e32 v131, v130, v130
	v_add_f32_e32 v130, v134, v131
	v_mul_f32_e32 v131, v177, v177
	v_mul_f32_e32 v134, v143, v143
	v_fmac_f32_e32 v131, v176, v176
	v_fmac_f32_e32 v134, v142, v142
	v_add_f32_e32 v131, v131, v134
	v_add_f32_e32 v130, v130, v131
	v_add_f32_e32 v128, v128, v130
	ds_bpermute_b32 v130, v152, v128
	v_cvt_pk_bf16_f32 v138, v176, v177
	v_cvt_pk_bf16_f32 v139, v142, v143
	global_store_dwordx4 v[186:187], v[136:139], off offset:256 nt
	ds_bpermute_b32 v135, v225, v129
	s_waitcnt lgkmcnt(1)
	v_add_f32_e32 v136, v128, v130
	ds_bpermute_b32 v137, v225, v136
	v_and_b32_e32 v130, 15, v223
	v_and_b32_e32 v128, 0xffffff80, v222
	v_lshlrev_b32_e32 v152, 2, v130
	v_add_u32_e32 v128, v166, v128
	v_lshl_add_u64 v[130:131], s[18:19], 0, v[152:153]
	s_and_saveexec_b64 s[4:5], vcc
	s_xor_b64 s[24:25], exec, s[4:5]
	s_cbranch_execz .LBB0_433
	v_ashrrev_i32_e32 v138, 6, v222
	v_cmp_lt_i32_e32 vcc, 1, v138
	s_mov_b64 s[36:37], 0
	s_and_saveexec_b64 s[4:5], vcc
	s_xor_b64 s[38:39], exec, s[4:5]
	s_cbranch_execnz .LBB0_454
	s_or_saveexec_b64 s[38:39], s[38:39]
	v_cmp_ne_u32_e32 vcc, 1, v138
	s_xor_b64 exec, exec, s[38:39]
	s_cbranch_execnz .LBB0_457

; __device__ __forceinline__ unsigned cvt_pk_bf16(float lo, float hi) { unsigned r; asm volatile("v_cvt_pk_bf16_f32 %0, %1, %2" : "=v"(r) : "v"(lo), "v"(hi)); return r; }
; __device__ __forceinline__ float bflo(unsigned w) { return __uint_as_float(w << 16); }
; __device__ __forceinline__ float bfhi(unsigned w) { return __uint_as_float(w & 0xffff0000u); }
; template <bool RD32>
; __device__ __forceinline__ void res_rows(const float* __restrict__ xold32, const bf16_t* __restrict__ xoldb, bf16_t* __restrict__ xb, float* __restrict__ ssq, const f32x4 (&acc)[2][2][4][2], int row0, int col0, int slot) {
;     ...
;     auto ld = [&](size_t o, f32x4& a, f32x4& b) { if (RD32) { a = *(const f32x4*)(xold32 + o); b = *(const f32x4*)(xold32 + o + 4); }
;         else { const u32x4 w = *(const u32x4*)(xoldb + o); a = (f32x4){bflo(w.x), bfhi(w.x), bflo(w.y), bfhi(w.y)}; b = (f32x4){bflo(w.z), bfhi(w.z), bflo(w.w), bfhi(w.w)}; } };
; #pragma unroll
;     for (int bj = 0; bj < 2; ++bj) ld((size_t)row0 * D + col0 + bj * HALF, xo[0][bj][0], xo[0][bj][1]);
; #pragma unroll
;     for (int idx = 0; idx < 8; ++idx) {
;         const int ai = idx >> 2, m = idx & 3; const int r = row0 + ai * HALF + m * 16; const size_t off = (size_t)r * D + col0;
;         if (idx < 7) { const int ai2 = (idx + 1) >> 2, m2 = (idx + 1) & 3; const size_t off2 = (size_t)(row0 + ai2 * HALF + m2 * 16) * D + col0;
; #pragma unroll
;             for (int bj = 0; bj < 2; ++bj) ld(off2 + bj * HALF, xo[(idx + 1) & 1][bj][0], xo[(idx + 1) & 1][bj][1]); }
;         float ss = 0.f;
; #pragma unroll
;         for (int bj = 0; bj < 2; ++bj) { const f32x4 x0 = xo[idx & 1][bj][0] + acc[ai][bj][m][0], x1 = xo[idx & 1][bj][1] + acc[ai][bj][m][1];
;             u32x4 w; w.x = cvt_pk_bf16(x0[0], x0[1]); w.y = cvt_pk_bf16(x0[2], x0[3]); w.z = cvt_pk_bf16(x1[0], x1[1]); w.w = cvt_pk_bf16(x1[2], x1[3]);
;             *(u32x4*)(xb + off + bj * HALF) = w;
;             ss += ((x0[0] * x0[0] + x0[1] * x0[1]) + (x0[2] * x0[2] + x0[3] * x0[3])) + ((x1[0] * x1[0] + x1[1] * x1[1]) + (x1[2] * x1[2] + x1[3] * x1[3])); }
;         ss += __shfl_xor(ss, 16); ss += __shfl_xor(ss, 32);
;         ssv[idx] = ss;
;     }
.LBB0_436:
.LBB0_437:
	v_readlane_b32 s4, v248, 0
	v_lshlrev_b64 v[128:129], 12, v[166:167]
	v_readlane_b32 s5, v248, 1
	v_lshlrev_b64 v[130:131], 2, v[132:133]
	v_ashrrev_i32_e32 v173, 31, v172
	v_lshl_add_u64 v[128:129], s[4:5], 0, v[128:129]
	v_lshl_add_u64 v[128:129], v[128:129], 0, v[130:131]
	global_load_dwordx4 v[180:183], v[128:129], off offset:16 nt
	global_load_dwordx4 v[184:187], v[128:129], off nt
	global_load_dwordx4 v[188:191], v[128:129], off offset:528 nt
	global_load_dwordx4 v[192:195], v[128:129], off offset:512 nt
	v_lshl_add_u64 v[178:179], s[4:5], 0, v[130:131]
	v_lshlrev_b64 v[128:129], 12, v[172:173]
	v_lshl_add_u64 v[176:177], v[132:133], 1, s[58:59]
	v_lshl_add_u64 v[132:133], v[178:179], 0, v[128:129]
	s_waitcnt lgkmcnt(0)
	global_load_dwordx4 v[136:139], v[132:133], off offset:16 nt
	global_load_dwordx4 v[140:143], v[132:133], off nt
	global_load_dwordx4 v[128:131], v[132:133], off offset:528 nt
	s_nop 0
	global_load_dwordx4 v[132:135], v[132:133], off offset:512 nt
	v_lshl_add_u64 v[174:175], v[176:177], 0, v[174:175]
	v_ashrrev_i32_e32 v171, 31, v170
	v_lshlrev_b64 v[172:173], 11, v[172:173]
	v_lshl_add_u64 v[172:173], v[176:177], 0, v[172:173]
	v_ashrrev_i32_e32 v169, 31, v168
	v_readlane_b32 s18, v248, 14
	v_readlane_b32 s19, v248, 15
	v_readlane_b32 s18, v246, 41
	v_readlane_b32 s19, v246, 42
	v_readlane_b32 s6, v248, 2
	v_readlane_b32 s7, v248, 3
	v_readlane_b32 s8, v248, 4
	v_readlane_b32 s9, v248, 5
	v_readlane_b32 s10, v248, 6
	v_readlane_b32 s11, v248, 7
	v_readlane_b32 s12, v248, 8
	v_readlane_b32 s13, v248, 9
	v_readlane_b32 s14, v248, 10
	v_readlane_b32 s15, v248, 11
	v_readlane_b32 s16, v248, 12
	v_readlane_b32 s17, v248, 13
	s_waitcnt vmcnt(0)
	v_pk_add_f32 v[180:181], v[120:121], v[180:181]
	v_pk_add_f32 v[126:127], v[126:127], v[186:187]
	v_pk_add_f32 v[124:125], v[124:125], v[184:185]
	v_pk_add_f32 v[182:183], v[122:123], v[182:183]
	v_cvt_pk_bf16_f32 v120, v124, v125
	v_cvt_pk_bf16_f32 v121, v126, v127
	v_cvt_pk_bf16_f32 v122, v180, v181
	v_pk_add_f32 v[118:119], v[118:119], v[194:195]
	v_cvt_pk_bf16_f32 v123, v182, v183
	global_store_dwordx4 v[174:175], v[120:123], off nt
	v_pk_add_f32 v[116:117], v[116:117], v[192:193]
	v_pk_add_f32 v[110:111], v[110:111], v[142:143]
	v_mul_f32_e32 v120, v125, v125
	v_mul_f32_e32 v121, v127, v127
	v_fmac_f32_e32 v120, v124, v124
	v_fmac_f32_e32 v121, v126, v126
	v_add_f32_e32 v120, v120, v121
	v_mul_f32_e32 v121, v181, v181
	v_mul_f32_e32 v122, v183, v183
	v_fmac_f32_e32 v121, v180, v180
	v_fmac_f32_e32 v122, v182, v182
	v_add_f32_e32 v121, v121, v122
	v_pk_add_f32 v[122:123], v[112:113], v[188:189]
	v_cvt_pk_bf16_f32 v112, v116, v117
	v_cvt_pk_bf16_f32 v113, v118, v119
	v_add_f32_e32 v124, v120, v121
	v_pk_add_f32 v[120:121], v[114:115], v[190:191]
	v_cvt_pk_bf16_f32 v114, v122, v123
	v_pk_add_f32 v[108:109], v[108:109], v[140:141]
	v_cvt_pk_bf16_f32 v115, v120, v121
	global_store_dwordx4 v[174:175], v[112:115], off offset:256 nt
	v_pk_add_f32 v[136:137], v[104:105], v[136:137]
	v_pk_add_f32 v[138:139], v[106:107], v[138:139]
	v_mul_f32_e32 v112, v117, v117
	v_mul_f32_e32 v113, v119, v119
	v_fmac_f32_e32 v112, v116, v116
	v_fmac_f32_e32 v113, v118, v118
	v_add_f32_e32 v112, v112, v113
	v_mul_f32_e32 v113, v123, v123
	v_mul_f32_e32 v114, v121, v121
	v_fmac_f32_e32 v113, v122, v122
	v_fmac_f32_e32 v114, v120, v120
	v_add_f32_e32 v113, v113, v114
	v_and_b32_e32 v114, 64, v209
	v_add_f32_e32 v112, v112, v113
	v_xor_b32_e32 v113, 16, v209
	v_add_u32_e32 v114, 64, v114
	v_cmp_lt_i32_e32 vcc, v113, v114
	v_add_f32_e32 v112, v124, v112
	v_pk_add_f32 v[102:103], v[102:103], v[134:135]
	v_cndmask_b32_e32 v113, v209, v113, vcc
	v_lshlrev_b32_e32 v152, 2, v113
	ds_bpermute_b32 v113, v152, v112
	v_pk_add_f32 v[100:101], v[100:101], v[132:133]
	s_waitcnt lgkmcnt(0)
	v_add_f32_e32 v174, v112, v113
	v_xor_b32_e32 v112, 32, v209
	v_cmp_lt_i32_e32 vcc, v112, v114
	s_nop 1
	v_cndmask_b32_e32 v112, v209, v112, vcc
	v_lshlrev_b32_e32 v180, 2, v112
	v_lshlrev_b64 v[112:113], 12, v[170:171]
	v_lshl_add_u64 v[116:117], v[178:179], 0, v[112:113]
	global_load_dwordx4 v[120:123], v[116:117], off offset:16 nt
	global_load_dwordx4 v[124:127], v[116:117], off nt
	global_load_dwordx4 v[112:115], v[116:117], off offset:528 nt
	s_nop 0
	global_load_dwordx4 v[116:119], v[116:117], off offset:512 nt
	v_cvt_pk_bf16_f32 v104, v108, v109
	v_cvt_pk_bf16_f32 v105, v110, v111
	v_cvt_pk_bf16_f32 v106, v136, v137
	v_cvt_pk_bf16_f32 v107, v138, v139
	global_store_dwordx4 v[172:173], v[104:107], off nt
	ds_bpermute_b32 v175, v180, v174
	v_cmp_lt_u32_e32 vcc, 63, v222
	v_mul_f32_e32 v104, v109, v109
	v_mul_f32_e32 v105, v111, v111
	v_fmac_f32_e32 v104, v108, v108
	v_fmac_f32_e32 v105, v110, v110
	v_add_f32_e32 v104, v104, v105
	v_mul_f32_e32 v105, v137, v137
	v_mul_f32_e32 v106, v139, v139
	v_fmac_f32_e32 v105, v136, v136
	v_fmac_f32_e32 v106, v138, v138
	v_add_f32_e32 v105, v105, v106
	v_pk_add_f32 v[106:107], v[96:97], v[128:129]
	v_cvt_pk_bf16_f32 v96, v100, v101
	v_cvt_pk_bf16_f32 v97, v102, v103
	v_add_f32_e32 v108, v104, v105
	v_pk_add_f32 v[104:105], v[98:99], v[130:131]
	v_cvt_pk_bf16_f32 v98, v106, v107
	v_lshlrev_b64 v[130:131], 11, v[170:171]
	v_cvt_pk_bf16_f32 v99, v104, v105
	global_store_dwordx4 v[172:173], v[96:99], off offset:256 nt
	v_lshl_add_u64 v[130:131], v[176:177], 0, v[130:131]
	s_waitcnt vmcnt(5)
	v_pk_add_f32 v[120:121], v[88:89], v[120:121]
	v_mul_f32_e32 v96, v101, v101
	v_mul_f32_e32 v97, v103, v103
	v_fmac_f32_e32 v96, v100, v100
	v_fmac_f32_e32 v97, v102, v102
	v_add_f32_e32 v96, v96, v97
	v_mul_f32_e32 v97, v107, v107
	v_mul_f32_e32 v98, v105, v105
	v_fmac_f32_e32 v97, v106, v106
	v_fmac_f32_e32 v98, v104, v104
	v_add_f32_e32 v97, v97, v98
	v_add_f32_e32 v96, v96, v97
	v_add_f32_e32 v96, v108, v96
	ds_bpermute_b32 v97, v152, v96
	s_waitcnt vmcnt(4)
; __device__ __forceinline__ unsigned cvt_pk_bf16(float lo, float hi) { unsigned r; asm volatile("v_cvt_pk_bf16_f32 %0, %1, %2" : "=v"(r) : "v"(lo), "v"(hi)); return r; }
; template <bool RD32>
; __device__ __forceinline__ void res_rows(const float* __restrict__ xold32, const bf16_t* __restrict__ xoldb, bf16_t* __restrict__ xb, float* __restrict__ ssq, const f32x4 (&acc)[2][2][4][2], int row0, int col0, int slot) {
;     ...
;     for (int idx = 0; idx < 8; ++idx) {
;         const int ai = idx >> 2, m = idx & 3; const int r = row0 + ai * HALF + m * 16; const size_t off = (size_t)r * D + col0;
;         if (idx < 7) { const int ai2 = (idx + 1) >> 2, m2 = (idx + 1) & 3; const size_t off2 = (size_t)(row0 + ai2 * HALF + m2 * 16) * D + col0;
; #pragma unroll
;             for (int bj = 0; bj < 2; ++bj) ld(off2 + bj * HALF, xo[(idx + 1) & 1][bj][0], xo[(idx + 1) & 1][bj][1]); }
;         float ss = 0.f;
; #pragma unroll
;         for (int bj = 0; bj < 2; ++bj) { const f32x4 x0 = xo[idx & 1][bj][0] + acc[ai][bj][m][0], x1 = xo[idx & 1][bj][1] + acc[ai][bj][m][1];
;             u32x4 w; w.x = cvt_pk_bf16(x0[0], x0[1]); w.y = cvt_pk_bf16(x0[2], x0[3]); w.z = cvt_pk_bf16(x1[0], x1[1]); w.w = cvt_pk_bf16(x1[2], x1[3]);
;             *(u32x4*)(xb + off + bj * HALF) = w;
;             ss += ((x0[0] * x0[0] + x0[1] * x0[1]) + (x0[2] * x0[2] + x0[3] * x0[3])) + ((x1[0] * x1[0] + x1[1] * x1[1]) + (x1[2] * x1[2] + x1[3] * x1[3])); }
;         ss += __shfl_xor(ss, 16); ss += __shfl_xor(ss, 32);
;         ssv[idx] = ss;
;     }
	v_pk_add_f32 v[94:95], v[94:95], v[126:127]
	v_pk_add_f32 v[92:93], v[92:93], v[124:125]
	v_pk_add_f32 v[122:123], v[90:91], v[122:123]
	s_waitcnt vmcnt(2)
	v_pk_add_f32 v[86:87], v[86:87], v[118:119]
	s_waitcnt lgkmcnt(0)
	v_add_f32_e32 v129, v96, v97
	v_lshlrev_b64 v[96:97], 12, v[168:169]
	v_lshl_add_u64 v[100:101], v[178:179], 0, v[96:97]
	global_load_dwordx4 v[104:107], v[100:101], off offset:16 nt
	global_load_dwordx4 v[108:111], v[100:101], off nt
	global_load_dwordx4 v[96:99], v[100:101], off offset:528 nt
	s_nop 0
	global_load_dwordx4 v[100:103], v[100:101], off offset:512 nt
	v_cvt_pk_bf16_f32 v88, v92, v93
	v_cvt_pk_bf16_f32 v89, v94, v95
	v_cvt_pk_bf16_f32 v90, v120, v121
	v_cvt_pk_bf16_f32 v91, v122, v123
	global_store_dwordx4 v[130:131], v[88:91], off nt
	v_pk_add_f32 v[84:85], v[84:85], v[116:117]
	v_lshlrev_b64 v[116:117], 11, v[168:169]
	v_mul_f32_e32 v88, v93, v93
	v_mul_f32_e32 v89, v95, v95
	v_fmac_f32_e32 v88, v92, v92
	v_fmac_f32_e32 v89, v94, v94
	v_add_f32_e32 v88, v88, v89
	v_mul_f32_e32 v89, v121, v121
	v_mul_f32_e32 v90, v123, v123
	v_fmac_f32_e32 v89, v120, v120
	v_fmac_f32_e32 v90, v122, v122
	v_add_f32_e32 v89, v89, v90
	v_pk_add_f32 v[90:91], v[80:81], v[112:113]
	v_cvt_pk_bf16_f32 v80, v84, v85
	v_cvt_pk_bf16_f32 v81, v86, v87
	v_add_f32_e32 v92, v88, v89
	v_pk_add_f32 v[88:89], v[82:83], v[114:115]
	v_cvt_pk_bf16_f32 v82, v90, v91
	v_add_u32_e32 v112, 0x80, v166
	v_cvt_pk_bf16_f32 v83, v88, v89
	global_store_dwordx4 v[130:131], v[80:83], off offset:256 nt
	v_ashrrev_i32_e32 v113, 31, v112
	v_lshl_add_u64 v[116:117], v[176:177], 0, v[116:117]
	v_mul_f32_e32 v80, v85, v85
	v_mul_f32_e32 v81, v87, v87
	v_fmac_f32_e32 v80, v84, v84
	v_fmac_f32_e32 v81, v86, v86
	v_add_f32_e32 v80, v80, v81
	v_mul_f32_e32 v81, v91, v91
	v_mul_f32_e32 v82, v89, v89
	v_fmac_f32_e32 v81, v90, v90
	v_fmac_f32_e32 v82, v88, v88
	v_add_f32_e32 v81, v81, v82
	v_add_f32_e32 v80, v80, v81
	v_add_f32_e32 v80, v92, v80
	ds_bpermute_b32 v81, v152, v80
	ds_bpermute_b32 v132, v180, v129
	s_waitcnt lgkmcnt(1)
	v_add_f32_e32 v114, v80, v81
	v_lshlrev_b64 v[80:81], 12, v[112:113]
	v_lshl_add_u64 v[84:85], v[178:179], 0, v[80:81]
	global_load_dwordx4 v[88:91], v[84:85], off offset:16 nt
	global_load_dwordx4 v[92:95], v[84:85], off nt
	global_load_dwordx4 v[80:83], v[84:85], off offset:528 nt
	s_nop 0
	global_load_dwordx4 v[84:87], v[84:85], off offset:512 nt
	ds_bpermute_b32 v115, v180, v114
	s_waitcnt vmcnt(9)
	v_pk_add_f32 v[104:105], v[72:73], v[104:105]
	s_waitcnt vmcnt(8)
	v_pk_add_f32 v[78:79], v[78:79], v[110:111]
	v_pk_add_f32 v[76:77], v[76:77], v[108:109]
	v_pk_add_f32 v[106:107], v[74:75], v[106:107]
	v_cvt_pk_bf16_f32 v72, v76, v77
	v_cvt_pk_bf16_f32 v73, v78, v79
	v_cvt_pk_bf16_f32 v74, v104, v105
	s_waitcnt vmcnt(6)
	v_pk_add_f32 v[70:71], v[70:71], v[102:103]
	v_cvt_pk_bf16_f32 v75, v106, v107
	global_store_dwordx4 v[116:117], v[72:75], off nt
	v_pk_add_f32 v[68:69], v[68:69], v[100:101]
	s_waitcnt vmcnt(4)
	v_pk_add_f32 v[88:89], v[56:57], v[88:89]
	v_mul_f32_e32 v72, v77, v77
	v_mul_f32_e32 v73, v79, v79
	v_fmac_f32_e32 v72, v76, v76
	v_fmac_f32_e32 v73, v78, v78
	v_add_f32_e32 v72, v72, v73
	v_mul_f32_e32 v73, v105, v105
	v_mul_f32_e32 v74, v107, v107
	v_fmac_f32_e32 v73, v104, v104
	v_fmac_f32_e32 v74, v106, v106
	v_add_f32_e32 v73, v73, v74
	v_pk_add_f32 v[74:75], v[64:65], v[96:97]
	v_cvt_pk_bf16_f32 v64, v68, v69
	v_cvt_pk_bf16_f32 v65, v70, v71
	v_add_f32_e32 v76, v72, v73
	v_pk_add_f32 v[72:73], v[66:67], v[98:99]
	v_cvt_pk_bf16_f32 v66, v74, v75
	v_add_u32_e32 v96, 0x90, v166
	v_cvt_pk_bf16_f32 v67, v72, v73
	global_store_dwordx4 v[116:117], v[64:67], off offset:256 nt
	v_ashrrev_i32_e32 v97, 31, v96
	v_lshlrev_b64 v[98:99], 11, v[112:113]
	v_mul_f32_e32 v64, v69, v69
	v_mul_f32_e32 v65, v71, v71
	v_fmac_f32_e32 v64, v68, v68
	v_fmac_f32_e32 v65, v70, v70
	v_add_f32_e32 v64, v64, v65
	v_mul_f32_e32 v65, v75, v75
	v_mul_f32_e32 v66, v73, v73
	v_fmac_f32_e32 v65, v74, v74
	v_fmac_f32_e32 v66, v72, v72
	v_add_f32_e32 v65, v65, v66
	v_add_f32_e32 v64, v64, v65
	v_add_f32_e32 v64, v76, v64
	ds_bpermute_b32 v65, v152, v64
	v_lshl_add_u64 v[98:99], v[176:177], 0, v[98:99]
	s_waitcnt vmcnt(4)
	v_pk_add_f32 v[62:63], v[62:63], v[94:95]
	v_pk_add_f32 v[60:61], v[60:61], v[92:93]
	v_pk_add_f32 v[90:91], v[58:59], v[90:91]
	s_waitcnt lgkmcnt(0)
	v_add_f32_e32 v100, v64, v65
	v_lshlrev_b64 v[64:65], 12, v[96:97]
	v_lshl_add_u64 v[68:69], v[178:179], 0, v[64:65]
	global_load_dwordx4 v[72:75], v[68:69], off offset:16 nt
	global_load_dwordx4 v[76:79], v[68:69], off nt
	global_load_dwordx4 v[64:67], v[68:69], off offset:528 nt
	s_nop 0
	global_load_dwordx4 v[68:71], v[68:69], off offset:512 nt
	v_cvt_pk_bf16_f32 v56, v60, v61
	v_cvt_pk_bf16_f32 v57, v62, v63
	v_cvt_pk_bf16_f32 v58, v88, v89
	v_cvt_pk_bf16_f32 v59, v90, v91
	global_store_dwordx4 v[98:99], v[56:59], off nt
	s_waitcnt vmcnt(7)
	v_pk_add_f32 v[54:55], v[54:55], v[86:87]
	v_pk_add_f32 v[52:53], v[52:53], v[84:85]
	v_mul_f32_e32 v56, v61, v61
	v_mul_f32_e32 v57, v63, v63
	v_fmac_f32_e32 v56, v60, v60
	v_fmac_f32_e32 v57, v62, v62
	v_add_f32_e32 v56, v56, v57
	v_mul_f32_e32 v57, v89, v89
	v_mul_f32_e32 v58, v91, v91
	v_fmac_f32_e32 v57, v88, v88
	v_fmac_f32_e32 v58, v90, v90
	v_add_f32_e32 v57, v57, v58
	v_pk_add_f32 v[58:59], v[48:49], v[80:81]
	v_cvt_pk_bf16_f32 v48, v52, v53
	v_cvt_pk_bf16_f32 v49, v54, v55
	v_add_f32_e32 v60, v56, v57
	v_pk_add_f32 v[56:57], v[50:51], v[82:83]
	v_cvt_pk_bf16_f32 v50, v58, v59
	v_add_u32_e32 v80, 0xa0, v166
	v_cvt_pk_bf16_f32 v51, v56, v57
	global_store_dwordx4 v[98:99], v[48:51], off offset:256 nt
	v_ashrrev_i32_e32 v81, 31, v80
	v_lshlrev_b64 v[84:85], 11, v[96:97]
	v_mul_f32_e32 v48, v53, v53
	v_mul_f32_e32 v49, v55, v55
	v_fmac_f32_e32 v48, v52, v52
	v_fmac_f32_e32 v49, v54, v54
	v_add_f32_e32 v48, v48, v49
	v_mul_f32_e32 v49, v59, v59
	v_mul_f32_e32 v50, v57, v57
	v_fmac_f32_e32 v49, v58, v58
	v_fmac_f32_e32 v50, v56, v56
	v_add_f32_e32 v49, v49, v50
	v_add_f32_e32 v48, v48, v49
	v_add_f32_e32 v48, v60, v48
	ds_bpermute_b32 v49, v152, v48
	v_lshl_add_u64 v[84:85], v[176:177], 0, v[84:85]
	ds_bpermute_b32 v101, v180, v100
	s_waitcnt lgkmcnt(1)
; __device__ __forceinline__ unsigned cvt_pk_bf16(float lo, float hi) { unsigned r; asm volatile("v_cvt_pk_bf16_f32 %0, %1, %2" : "=v"(r) : "v"(lo), "v"(hi)); return r; }
; template <bool RD32>
; __device__ __forceinline__ void res_rows(const float* __restrict__ xold32, const bf16_t* __restrict__ xoldb, bf16_t* __restrict__ xb, float* __restrict__ ssq, const f32x4 (&acc)[2][2][4][2], int row0, int col0, int slot) {
;     ...
;     for (int idx = 0; idx < 8; ++idx) {
;         const int ai = idx >> 2, m = idx & 3; const int r = row0 + ai * HALF + m * 16; const size_t off = (size_t)r * D + col0;
;         if (idx < 7) { const int ai2 = (idx + 1) >> 2, m2 = (idx + 1) & 3; const size_t off2 = (size_t)(row0 + ai2 * HALF + m2 * 16) * D + col0;
; #pragma unroll
;             for (int bj = 0; bj < 2; ++bj) ld(off2 + bj * HALF, xo[(idx + 1) & 1][bj][0], xo[(idx + 1) & 1][bj][1]); }
;         float ss = 0.f;
; #pragma unroll
;         for (int bj = 0; bj < 2; ++bj) { const f32x4 x0 = xo[idx & 1][bj][0] + acc[ai][bj][m][0], x1 = xo[idx & 1][bj][1] + acc[ai][bj][m][1];
;             u32x4 w; w.x = cvt_pk_bf16(x0[0], x0[1]); w.y = cvt_pk_bf16(x0[2], x0[3]); w.z = cvt_pk_bf16(x1[0], x1[1]); w.w = cvt_pk_bf16(x1[2], x1[3]);
;             *(u32x4*)(xb + off + bj * HALF) = w;
;             ss += ((x0[0] * x0[0] + x0[1] * x0[1]) + (x0[2] * x0[2] + x0[3] * x0[3])) + ((x1[0] * x1[0] + x1[1] * x1[1]) + (x1[2] * x1[2] + x1[3] * x1[3])); }
;         ss += __shfl_xor(ss, 16); ss += __shfl_xor(ss, 32);
;         ssv[idx] = ss;
;     }
;     const int fq = slot >> 6;
; #pragma unroll
;     for (int j = 0; j < 2; ++j) { const float v = fq == 0 ? ssv[j] : fq == 1 ? ssv[2 + j] : fq == 2 ? ssv[4 + j] : ssv[6 + j]; const int idx = 2 * fq + j;
;         ssq[(size_t)(row0 + (idx >> 2) * HALF + (idx & 3) * 16) * 16 + (slot & 15)] = v; }
	v_add_f32_e32 v82, v48, v49
	v_lshlrev_b64 v[48:49], 12, v[80:81]
	v_lshl_add_u64 v[60:61], v[178:179], 0, v[48:49]
	global_load_dwordx4 v[48:51], v[60:61], off offset:16 nt
	global_load_dwordx4 v[52:55], v[60:61], off nt
	global_load_dwordx4 v[56:59], v[60:61], off offset:528 nt
	s_nop 0
	global_load_dwordx4 v[60:63], v[60:61], off offset:512 nt
	ds_bpermute_b32 v83, v180, v82
	s_waitcnt vmcnt(9)
	v_pk_add_f32 v[72:73], v[40:41], v[72:73]
	s_waitcnt vmcnt(8)
	v_pk_add_f32 v[46:47], v[46:47], v[78:79]
	v_pk_add_f32 v[44:45], v[44:45], v[76:77]
	v_pk_add_f32 v[74:75], v[42:43], v[74:75]
	v_cvt_pk_bf16_f32 v40, v44, v45
	v_cvt_pk_bf16_f32 v41, v46, v47
	v_cvt_pk_bf16_f32 v42, v72, v73
	s_waitcnt vmcnt(6)
	v_pk_add_f32 v[38:39], v[38:39], v[70:71]
	v_cvt_pk_bf16_f32 v43, v74, v75
	global_store_dwordx4 v[84:85], v[40:43], off nt
	v_pk_add_f32 v[36:37], v[36:37], v[68:69]
	v_lshlrev_b64 v[68:69], 11, v[80:81]
	v_mul_f32_e32 v40, v45, v45
	v_mul_f32_e32 v41, v47, v47
	v_fmac_f32_e32 v40, v44, v44
	v_fmac_f32_e32 v41, v46, v46
	v_add_f32_e32 v40, v40, v41
	v_mul_f32_e32 v41, v73, v73
	v_mul_f32_e32 v42, v75, v75
	v_fmac_f32_e32 v41, v72, v72
	v_fmac_f32_e32 v42, v74, v74
	v_add_f32_e32 v41, v41, v42
	v_pk_add_f32 v[42:43], v[32:33], v[64:65]
	v_cvt_pk_bf16_f32 v32, v36, v37
	v_cvt_pk_bf16_f32 v33, v38, v39
	v_add_f32_e32 v44, v40, v41
	v_pk_add_f32 v[40:41], v[34:35], v[66:67]
	v_cvt_pk_bf16_f32 v34, v42, v43
	v_lshl_add_u64 v[68:69], v[176:177], 0, v[68:69]
	v_cvt_pk_bf16_f32 v35, v40, v41
	global_store_dwordx4 v[84:85], v[32:35], off offset:256 nt
	s_waitcnt vmcnt(5)
	v_pk_add_f32 v[48:49], v[24:25], v[48:49]
	v_mul_f32_e32 v32, v37, v37
	v_mul_f32_e32 v33, v39, v39
	v_fmac_f32_e32 v32, v36, v36
	v_fmac_f32_e32 v33, v38, v38
	v_add_f32_e32 v32, v32, v33
	v_mul_f32_e32 v33, v43, v43
	v_mul_f32_e32 v34, v41, v41
	v_fmac_f32_e32 v33, v42, v42
	v_fmac_f32_e32 v34, v40, v40
	v_add_f32_e32 v33, v33, v34
	v_add_f32_e32 v32, v32, v33
	v_add_f32_e32 v32, v44, v32
	ds_bpermute_b32 v33, v152, v32
	v_add_u32_e32 v44, 0xb0, v166
	v_ashrrev_i32_e32 v45, 31, v44
	s_waitcnt vmcnt(4)
	v_pk_add_f32 v[30:31], v[30:31], v[54:55]
	v_pk_add_f32 v[28:29], v[28:29], v[52:53]
	s_waitcnt lgkmcnt(0)
	v_add_f32_e32 v46, v32, v33
	v_lshlrev_b64 v[32:33], 12, v[44:45]
	v_lshl_add_u64 v[64:65], v[178:179], 0, v[32:33]
	global_load_dwordx4 v[36:39], v[64:65], off offset:16 nt
	global_load_dwordx4 v[40:43], v[64:65], off nt
	global_load_dwordx4 v[32:35], v[64:65], off offset:528 nt
	s_nop 0
	global_load_dwordx4 v[64:67], v[64:65], off offset:512 nt
	v_cvt_pk_bf16_f32 v24, v28, v29
	v_cvt_pk_bf16_f32 v25, v30, v31
	v_pk_add_f32 v[50:51], v[26:27], v[50:51]
	v_cvt_pk_bf16_f32 v26, v48, v49
	s_waitcnt vmcnt(6)
	v_pk_add_f32 v[22:23], v[22:23], v[62:63]
	v_cvt_pk_bf16_f32 v27, v50, v51
	global_store_dwordx4 v[68:69], v[24:27], off nt
	v_pk_add_f32 v[20:21], v[20:21], v[60:61]
	ds_bpermute_b32 v47, v180, v46
	v_mul_f32_e32 v24, v29, v29
	v_mul_f32_e32 v25, v31, v31
	v_fmac_f32_e32 v24, v28, v28
	v_fmac_f32_e32 v25, v30, v30
	v_add_f32_e32 v24, v24, v25
	v_mul_f32_e32 v25, v49, v49
	v_mul_f32_e32 v26, v51, v51
	v_fmac_f32_e32 v25, v48, v48
	v_fmac_f32_e32 v26, v50, v50
	v_add_f32_e32 v25, v25, v26
	v_pk_add_f32 v[26:27], v[16:17], v[56:57]
	v_cvt_pk_bf16_f32 v16, v20, v21
	v_cvt_pk_bf16_f32 v17, v22, v23
	v_add_f32_e32 v28, v24, v25
	v_pk_add_f32 v[24:25], v[18:19], v[58:59]
	v_cvt_pk_bf16_f32 v18, v26, v27
	s_waitcnt vmcnt(3)
	v_pk_add_f32 v[14:15], v[14:15], v[42:43]
	v_cvt_pk_bf16_f32 v19, v24, v25
	global_store_dwordx4 v[68:69], v[16:19], off offset:256 nt
	v_pk_add_f32 v[12:13], v[12:13], v[40:41]
	s_waitcnt vmcnt(2)
	v_pk_add_f32 v[6:7], v[6:7], v[66:67]
	v_mul_f32_e32 v16, v21, v21
	v_mul_f32_e32 v17, v23, v23
	v_fmac_f32_e32 v16, v20, v20
	v_fmac_f32_e32 v17, v22, v22
	v_add_f32_e32 v16, v16, v17
	v_mul_f32_e32 v17, v27, v27
	v_mul_f32_e32 v18, v25, v25
	v_fmac_f32_e32 v17, v26, v26
	v_fmac_f32_e32 v18, v24, v24
	v_add_f32_e32 v17, v17, v18
	v_lshlrev_b64 v[18:19], 11, v[44:45]
	v_lshl_add_u64 v[18:19], v[176:177], 0, v[18:19]
	v_pk_add_f32 v[22:23], v[8:9], v[36:37]
	v_cvt_pk_bf16_f32 v8, v12, v13
	v_cvt_pk_bf16_f32 v9, v14, v15
	v_pk_add_f32 v[20:21], v[10:11], v[38:39]
	v_cvt_pk_bf16_f32 v10, v22, v23
	v_pk_add_f32 v[4:5], v[4:5], v[64:65]
	v_cvt_pk_bf16_f32 v11, v20, v21
	global_store_dwordx4 v[18:19], v[8:11], off nt
	v_add_f32_e32 v16, v16, v17
	v_add_f32_e32 v16, v28, v16
	v_mul_f32_e32 v8, v13, v13
	v_mul_f32_e32 v9, v15, v15
	v_fmac_f32_e32 v8, v12, v12
	v_fmac_f32_e32 v9, v14, v14
	v_add_f32_e32 v8, v8, v9
	v_mul_f32_e32 v9, v23, v23
	v_mul_f32_e32 v10, v21, v21
	v_fmac_f32_e32 v9, v22, v22
	v_fmac_f32_e32 v10, v20, v20
	v_add_f32_e32 v9, v9, v10
	v_pk_add_f32 v[10:11], v[0:1], v[32:33]
	v_cvt_pk_bf16_f32 v0, v4, v5
	v_cvt_pk_bf16_f32 v1, v6, v7
	v_add_f32_e32 v12, v8, v9
	v_pk_add_f32 v[8:9], v[2:3], v[34:35]
	v_cvt_pk_bf16_f32 v2, v10, v11
	ds_bpermute_b32 v17, v152, v16
	v_cvt_pk_bf16_f32 v3, v8, v9
	global_store_dwordx4 v[18:19], v[0:3], off offset:256 nt
	s_waitcnt lgkmcnt(0)
	v_add_f32_e32 v16, v16, v17
	v_mul_f32_e32 v0, v5, v5
	v_mul_f32_e32 v1, v7, v7
	v_fmac_f32_e32 v0, v4, v4
	v_fmac_f32_e32 v1, v6, v6
	v_add_f32_e32 v0, v0, v1
	v_mul_f32_e32 v1, v11, v11
	v_mul_f32_e32 v2, v9, v9
	v_fmac_f32_e32 v1, v10, v10
	v_fmac_f32_e32 v2, v8, v8
	v_add_f32_e32 v1, v1, v2
	v_add_f32_e32 v0, v0, v1
	v_add_f32_e32 v0, v12, v0
	ds_bpermute_b32 v1, v152, v0
	ds_bpermute_b32 v17, v180, v16
	v_and_b32_e32 v2, 0xffffff80, v222
	v_add_u32_e32 v128, v166, v2
	v_and_b32_e32 v2, 15, v223
	s_waitcnt lgkmcnt(1)
	v_add_f32_e32 v0, v0, v1
	ds_bpermute_b32 v1, v180, v0
	v_lshlrev_b32_e32 v152, 2, v2
	v_lshl_add_u64 v[130:131], s[18:19], 0, v[152:153]
	s_and_saveexec_b64 s[4:5], vcc
	s_xor_b64 s[24:25], exec, s[4:5]
	s_cbranch_execz .LBB0_448
	v_ashrrev_i32_e32 v2, 6, v222
	v_cmp_lt_i32_e32 vcc, 1, v2
	s_mov_b64 s[36:37], 0
	s_and_saveexec_b64 s[4:5], vcc
	s_xor_b64 s[38:39], exec, s[4:5]
	s_cbranch_execnz .LBB0_461
	s_or_saveexec_b64 s[38:39], s[38:39]
	v_cmp_ne_u32_e32 vcc, 1, v2
	s_xor_b64 exec, exec, s[38:39]
	s_cbranch_execnz .LBB0_464

; __device__ __forceinline__ unsigned cvt_pk_bf16(float lo, float hi) { unsigned r; asm volatile("v_cvt_pk_bf16_f32 %0, %1, %2" : "=v"(r) : "v"(lo), "v"(hi)); return r; }
; __device__ __forceinline__ float bflo(unsigned w) { return __uint_as_float(w << 16); }
; __device__ __forceinline__ float bfhi(unsigned w) { return __uint_as_float(w & 0xffff0000u); }
; template <bool RD32>
; __device__ __forceinline__ void res_rows(const float* __restrict__ xold32, const bf16_t* __restrict__ xoldb, bf16_t* __restrict__ xb, float* __restrict__ ssq, const f32x4 (&acc)[2][2][4][2], int row0, int col0, int slot) {
;     f32x4 xo[2][2][2];
;     float ssv[8];
;     auto ld = [&](size_t o, f32x4& a, f32x4& b) { if (RD32) { a = *(const f32x4*)(xold32 + o); b = *(const f32x4*)(xold32 + o + 4); }
;         else { const u32x4 w = *(const u32x4*)(xoldb + o); a = (f32x4){bflo(w.x), bfhi(w.x), bflo(w.y), bfhi(w.y)}; b = (f32x4){bflo(w.z), bfhi(w.z), bflo(w.w), bfhi(w.w)}; } };
; #pragma unroll
;     for (int bj = 0; bj < 2; ++bj) ld((size_t)row0 * D + col0 + bj * HALF, xo[0][bj][0], xo[0][bj][1]);
; #pragma unroll
;     for (int idx = 0; idx < 8; ++idx) {
;         const int ai = idx >> 2, m = idx & 3; const int r = row0 + ai * HALF + m * 16; const size_t off = (size_t)r * D + col0;
;         if (idx < 7) { const int ai2 = (idx + 1) >> 2, m2 = (idx + 1) & 3; const size_t off2 = (size_t)(row0 + ai2 * HALF + m2 * 16) * D + col0;
; #pragma unroll
;             for (int bj = 0; bj < 2; ++bj) ld(off2 + bj * HALF, xo[(idx + 1) & 1][bj][0], xo[(idx + 1) & 1][bj][1]); }
;         float ss = 0.f;
; #pragma unroll
;         for (int bj = 0; bj < 2; ++bj) { const f32x4 x0 = xo[idx & 1][bj][0] + acc[ai][bj][m][0], x1 = xo[idx & 1][bj][1] + acc[ai][bj][m][1];
;             u32x4 w; w.x = cvt_pk_bf16(x0[0], x0[1]); w.y = cvt_pk_bf16(x0[2], x0[3]); w.z = cvt_pk_bf16(x1[0], x1[1]); w.w = cvt_pk_bf16(x1[2], x1[3]);
;             *(u32x4*)(xb + off + bj * HALF) = w;
;             ss += ((x0[0] * x0[0] + x0[1] * x0[1]) + (x0[2] * x0[2] + x0[3] * x0[3])) + ((x1[0] * x1[0] + x1[1] * x1[1]) + (x1[2] * x1[2] + x1[3] * x1[3])); }
;         ss += __shfl_xor(ss, 16); ss += __shfl_xor(ss, 32);
;         ssv[idx] = ss;
;     }
.LBB0_615:
	v_lshl_add_u32 v164, s51, 8, v174
	v_lshl_or_b32 v128, s50, 8, v176
	v_ashrrev_i32_e32 v165, 31, v164
	v_ashrrev_i32_e32 v129, 31, v128
	v_lshlrev_b64 v[166:167], 11, v[164:165]
	v_lshl_add_u64 v[130:131], s[58:59], 0, v[166:167]
	v_lshlrev_b64 v[128:129], 1, v[128:129]
	v_lshl_add_u64 v[130:131], v[130:131], 0, v[128:129]
	global_load_dwordx4 v[136:139], v[130:131], off nt
	global_load_dwordx4 v[140:143], v[130:131], off offset:256 nt
	v_or_b32_e32 v130, 16, v164
	v_ashrrev_i32_e32 v131, 31, v130
	v_lshl_add_u64 v[168:169], s[58:59], 0, v[128:129]
	v_lshlrev_b64 v[128:129], 11, v[130:131]
	v_lshl_add_u64 v[170:171], v[168:169], 0, v[128:129]
	global_load_dwordx4 v[128:131], v[170:171], off nt
	global_load_dwordx4 v[132:135], v[170:171], off offset:256 nt
	v_and_b32_e32 v172, 64, v209
	v_xor_b32_e32 v173, 16, v209
	v_add_u32_e32 v194, 64, v172
	v_or_b32_e32 v172, 32, v164
	v_or_b32_e32 v182, 48, v164
	v_cmp_lt_i32_e32 vcc, v173, v194
	v_ashrrev_i32_e32 v183, 31, v182
	v_lshlrev_b64 v[182:183], 11, v[182:183]
	v_cndmask_b32_e32 v180, v209, v173, vcc
	v_ashrrev_i32_e32 v173, 31, v172
	v_lshlrev_b64 v[172:173], 11, v[172:173]
	v_lshl_add_u64 v[166:167], v[168:169], 0, v[166:167]
	v_lshl_add_u64 v[172:173], v[168:169], 0, v[172:173]
	v_lshl_add_u64 v[168:169], v[168:169], 0, v[182:183]
	v_lshlrev_b32_e32 v180, 2, v180
	s_mov_b32 s14, 0x40000
	v_xor_b32_e32 v181, 32, v209
	s_lshl_b32 s29, s50, 2
	v_or_b32_e32 v179, s29, v177
	s_waitcnt vmcnt(0)
	v_lshlrev_b32_e32 v182, 16, v136
	v_and_b32_e32 v183, 0xffff0000, v136
	v_lshlrev_b32_e32 v136, 16, v137
	v_and_b32_e32 v137, 0xffff0000, v137
	v_lshlrev_b32_e32 v184, 16, v138
	v_and_b32_e32 v185, 0xffff0000, v138
	v_lshlrev_b32_e32 v138, 16, v139
	v_and_b32_e32 v139, 0xffff0000, v139
	v_lshlrev_b32_e32 v188, 16, v142
	v_and_b32_e32 v189, 0xffff0000, v142
	v_lshlrev_b32_e32 v142, 16, v143
	v_and_b32_e32 v143, 0xffff0000, v143
	v_lshlrev_b32_e32 v186, 16, v140
	v_and_b32_e32 v187, 0xffff0000, v140
	v_lshlrev_b32_e32 v140, 16, v141
	v_and_b32_e32 v141, 0xffff0000, v141
	v_pk_add_f32 v[126:127], v[126:127], v[136:137]
	v_pk_add_f32 v[124:125], v[124:125], v[182:183]
	v_pk_add_f32 v[136:137], v[122:123], v[138:139]
	v_pk_add_f32 v[138:139], v[120:121], v[184:185]
	v_pk_add_f32 v[142:143], v[110:111], v[142:143]
	v_pk_add_f32 v[184:185], v[108:109], v[188:189]
	v_cvt_pk_bf16_f32 v108, v124, v125
	v_cvt_pk_bf16_f32 v109, v126, v127
	v_cvt_pk_bf16_f32 v110, v138, v139
	v_cvt_pk_bf16_f32 v111, v136, v137
	v_pk_add_f32 v[140:141], v[118:119], v[140:141]
	v_pk_add_f32 v[182:183], v[116:117], v[186:187]
	global_store_dwordx4 v[166:167], v[108:111], off nt
	v_lshlrev_b32_e32 v190, 16, v128
	v_and_b32_e32 v191, 0xffff0000, v128
	v_cvt_pk_bf16_f32 v108, v182, v183
	v_cvt_pk_bf16_f32 v109, v140, v141
	v_cvt_pk_bf16_f32 v110, v184, v185
	v_cvt_pk_bf16_f32 v111, v142, v143
	global_load_dwordx4 v[116:119], v[172:173], off nt
	global_load_dwordx4 v[120:123], v[172:173], off offset:256 nt
	v_lshlrev_b32_e32 v128, 16, v129
	v_and_b32_e32 v129, 0xffff0000, v129
	v_lshlrev_b32_e32 v186, 16, v130
	v_and_b32_e32 v187, 0xffff0000, v130
	v_lshlrev_b32_e32 v130, 16, v131
	v_and_b32_e32 v131, 0xffff0000, v131
	v_lshlrev_b32_e32 v188, 16, v132
	v_and_b32_e32 v189, 0xffff0000, v132
	v_lshlrev_b32_e32 v192, 16, v134
	v_and_b32_e32 v193, 0xffff0000, v134
	v_lshlrev_b32_e32 v134, 16, v135
	v_and_b32_e32 v135, 0xffff0000, v135
	v_lshlrev_b32_e32 v132, 16, v133
	v_and_b32_e32 v133, 0xffff0000, v133
	v_pk_add_f32 v[114:115], v[114:115], v[128:129]
	v_pk_add_f32 v[112:113], v[112:113], v[190:191]
	v_pk_add_f32 v[128:129], v[106:107], v[130:131]
	v_pk_add_f32 v[130:131], v[104:105], v[186:187]
	v_pk_add_f32 v[186:187], v[100:101], v[188:189]
	v_pk_add_f32 v[134:135], v[98:99], v[134:135]
	v_pk_add_f32 v[188:189], v[96:97], v[192:193]
	global_store_dwordx4 v[166:167], v[108:111], off offset:256 nt
	v_cvt_pk_bf16_f32 v96, v112, v113
	v_cvt_pk_bf16_f32 v97, v114, v115
	v_cvt_pk_bf16_f32 v98, v130, v131
	v_cvt_pk_bf16_f32 v99, v128, v129
	v_pk_add_f32 v[132:133], v[102:103], v[132:133]
	global_store_dwordx4 v[170:171], v[96:99], off nt
	v_mul_f32_e32 v125, v125, v125
	v_mul_f32_e32 v127, v127, v127
	v_cvt_pk_bf16_f32 v96, v186, v187
	v_cvt_pk_bf16_f32 v97, v132, v133
	v_cvt_pk_bf16_f32 v98, v188, v189
	v_cvt_pk_bf16_f32 v99, v134, v135
	global_load_dwordx4 v[100:103], v[168:169], off nt
	global_load_dwordx4 v[104:107], v[168:169], off offset:256 nt
	v_mul_f32_e32 v139, v139, v139
	v_mul_f32_e32 v137, v137, v137
	v_mul_f32_e32 v183, v183, v183
	v_mul_f32_e32 v141, v141, v141
	v_mul_f32_e32 v185, v185, v185
	v_mul_f32_e32 v143, v143, v143
	v_fmac_f32_e32 v125, v124, v124
	v_fmac_f32_e32 v127, v126, v126
	v_fmac_f32_e32 v139, v138, v138
	v_fmac_f32_e32 v137, v136, v136
	v_fmac_f32_e32 v183, v182, v182
	v_fmac_f32_e32 v141, v140, v140
	v_fmac_f32_e32 v185, v184, v184
	v_fmac_f32_e32 v143, v142, v142
	v_add_f32_e32 v108, v125, v127
	v_add_f32_e32 v109, v139, v137
	v_add_f32_e32 v110, v183, v141
	v_add_f32_e32 v111, v185, v143
	v_add_f32_e32 v108, v108, v109
	v_add_f32_e32 v109, v110, v111
	v_mul_f32_e32 v190, v113, v113
	v_mul_f32_e32 v191, v115, v115
	v_mul_f32_e32 v192, v131, v131
	v_mul_f32_e32 v193, v129, v129
	v_add_f32_e32 v108, v108, v109
	v_fmac_f32_e32 v190, v112, v112
	v_fmac_f32_e32 v191, v114, v114
	v_fmac_f32_e32 v192, v130, v130
	v_fmac_f32_e32 v193, v128, v128
	ds_bpermute_b32 v109, v180, v108
	v_add_f32_e32 v112, v190, v191
	v_add_f32_e32 v110, v192, v193
	v_add_f32_e32 v127, v112, v110
	v_mul_f32_e32 v195, v187, v187
	v_mul_f32_e32 v196, v133, v133
	v_mul_f32_e32 v197, v189, v189
	v_fmac_f32_e32 v195, v186, v186
	v_fmac_f32_e32 v196, v132, v132
	v_fmac_f32_e32 v197, v188, v188
	v_add_f32_e32 v126, v195, v196
	global_store_dwordx4 v[170:171], v[96:99], off offset:256 nt
	s_waitcnt vmcnt(6)
; __device__ __forceinline__ unsigned cvt_pk_bf16(float lo, float hi) { unsigned r; asm volatile("v_cvt_pk_bf16_f32 %0, %1, %2" : "=v"(r) : "v"(lo), "v"(hi)); return r; }
; template <bool RD32>
; __device__ __forceinline__ void res_rows(const float* __restrict__ xold32, const bf16_t* __restrict__ xoldb, bf16_t* __restrict__ xb, float* __restrict__ ssq, const f32x4 (&acc)[2][2][4][2], int row0, int col0, int slot) {
;     ...
;     for (int idx = 0; idx < 8; ++idx) {
;         const int ai = idx >> 2, m = idx & 3; const int r = row0 + ai * HALF + m * 16; const size_t off = (size_t)r * D + col0;
;         if (idx < 7) { const int ai2 = (idx + 1) >> 2, m2 = (idx + 1) & 3; const size_t off2 = (size_t)(row0 + ai2 * HALF + m2 * 16) * D + col0;
; #pragma unroll
;             for (int bj = 0; bj < 2; ++bj) ld(off2 + bj * HALF, xo[(idx + 1) & 1][bj][0], xo[(idx + 1) & 1][bj][1]); }
;         float ss = 0.f;
; #pragma unroll
;         for (int bj = 0; bj < 2; ++bj) { const f32x4 x0 = xo[idx & 1][bj][0] + acc[ai][bj][m][0], x1 = xo[idx & 1][bj][1] + acc[ai][bj][m][1];
;             u32x4 w; w.x = cvt_pk_bf16(x0[0], x0[1]); w.y = cvt_pk_bf16(x0[2], x0[3]); w.z = cvt_pk_bf16(x1[0], x1[1]); w.w = cvt_pk_bf16(x1[2], x1[3]);
;             *(u32x4*)(xb + off + bj * HALF) = w;
;             ss += ((x0[0] * x0[0] + x0[1] * x0[1]) + (x0[2] * x0[2] + x0[3] * x0[3])) + ((x1[0] * x1[0] + x1[1] * x1[1]) + (x1[2] * x1[2] + x1[3] * x1[3])); }
;         ss += __shfl_xor(ss, 16); ss += __shfl_xor(ss, 32);
;         ssv[idx] = ss;
;     }
	v_lshlrev_b32_e32 v110, 16, v118
	v_and_b32_e32 v111, 0xffff0000, v118
	v_lshlrev_b32_e32 v112, 16, v119
	v_and_b32_e32 v113, 0xffff0000, v119
	s_waitcnt vmcnt(5)
	v_lshlrev_b32_e32 v118, 16, v122
	v_and_b32_e32 v119, 0xffff0000, v122
	v_pk_add_f32 v[118:119], v[80:81], v[118:119]
	v_mul_f32_e32 v80, v135, v135
	v_fmac_f32_e32 v80, v134, v134
	s_waitcnt lgkmcnt(0)
	v_add_f32_e32 v96, v108, v109
	v_lshlrev_b32_e32 v98, 16, v116
	v_and_b32_e32 v99, 0xffff0000, v116
	v_lshlrev_b32_e32 v108, 16, v117
	v_and_b32_e32 v109, 0xffff0000, v117
	v_lshlrev_b32_e32 v114, 16, v120
	v_and_b32_e32 v115, 0xffff0000, v120
	v_lshlrev_b32_e32 v116, 16, v121
	v_and_b32_e32 v117, 0xffff0000, v121
	v_lshlrev_b32_e32 v120, 16, v123
	v_and_b32_e32 v121, 0xffff0000, v123
	v_add_f32_e32 v80, v197, v80
	v_pk_add_f32 v[120:121], v[82:83], v[120:121]
	v_add_co_u32_e32 v82, vcc, s14, v166
	v_add_f32_e32 v80, v126, v80
	s_mov_b64 s[14:15], 0x40000
	v_pk_add_f32 v[122:123], v[94:95], v[108:109]
	v_pk_add_f32 v[98:99], v[92:93], v[98:99]
	v_pk_add_f32 v[90:91], v[90:91], v[112:113]
	v_pk_add_f32 v[88:89], v[88:89], v[110:111]
	v_cvt_pk_bf16_f32 v92, v98, v99
	v_cvt_pk_bf16_f32 v93, v122, v123
	v_pk_add_f32 v[124:125], v[84:85], v[114:115]
	v_cvt_pk_bf16_f32 v94, v88, v89
	v_cvt_pk_bf16_f32 v95, v90, v91
	v_addc_co_u32_e32 v83, vcc, 0, v167, vcc
	v_add_f32_e32 v84, v127, v80
	v_lshl_add_u64 v[80:81], v[166:167], 0, s[14:15]
	global_store_dwordx4 v[172:173], v[92:95], off nt
	v_pk_add_f32 v[116:117], v[86:87], v[116:117]
	v_mul_f32_e32 v97, v99, v99
	v_cvt_pk_bf16_f32 v92, v124, v125
	v_cvt_pk_bf16_f32 v93, v116, v117
	v_cvt_pk_bf16_f32 v94, v118, v119
	v_cvt_pk_bf16_f32 v95, v120, v121
	global_load_dwordx4 v[108:111], v[82:83], off nt
	global_load_dwordx4 v[112:115], v[80:81], off offset:256 nt
	s_waitcnt vmcnt(4)
	v_lshlrev_b32_e32 v132, 16, v106
	v_and_b32_e32 v133, 0xffff0000, v106
	v_fmac_f32_e32 v97, v98, v98
	v_mul_f32_e32 v98, v123, v123
	v_fmac_f32_e32 v98, v122, v122
	v_mul_f32_e32 v89, v89, v89
	v_pk_add_f32 v[122:123], v[64:65], v[132:133]
	v_mul_f32_e32 v64, v91, v91
	v_cmp_lt_i32_e32 vcc, v181, v194
	v_lshlrev_b32_e32 v106, 16, v107
	v_and_b32_e32 v107, 0xffff0000, v107
	s_mov_b32 s14, 0x48000
	v_fmac_f32_e32 v89, v88, v88
	v_fmac_f32_e32 v64, v90, v90
	v_cndmask_b32_e32 v85, v209, v181, vcc
	v_lshlrev_b32_e32 v126, 16, v100
	v_and_b32_e32 v127, 0xffff0000, v100
	v_lshlrev_b32_e32 v100, 16, v101
	v_and_b32_e32 v101, 0xffff0000, v101
	v_lshlrev_b32_e32 v128, 16, v102
	v_and_b32_e32 v129, 0xffff0000, v102
	v_lshlrev_b32_e32 v102, 16, v103
	v_and_b32_e32 v103, 0xffff0000, v103
	v_add_f32_e32 v97, v97, v98
	v_pk_add_f32 v[106:107], v[66:67], v[106:107]
	v_add_co_u32_e32 v66, vcc, s14, v166
	v_add_f32_e32 v64, v89, v64
	s_mov_b64 s[14:15], 0x48000
	v_lshlrev_b32_e32 v130, 16, v104
	v_and_b32_e32 v131, 0xffff0000, v104
	v_lshlrev_b32_e32 v104, 16, v105
	v_and_b32_e32 v105, 0xffff0000, v105
	global_store_dwordx4 v[172:173], v[92:95], off offset:256 nt
	v_pk_add_f32 v[98:99], v[74:75], v[102:103]
	v_addc_co_u32_e32 v67, vcc, 0, v167, vcc
	v_pk_add_f32 v[92:93], v[78:79], v[100:101]
	v_pk_add_f32 v[94:95], v[76:77], v[126:127]
	v_pk_add_f32 v[100:101], v[72:73], v[128:129]
	v_cvt_pk_bf16_f32 v72, v94, v95
	v_cvt_pk_bf16_f32 v73, v92, v93
	v_add_f32_e32 v88, v97, v64
	v_cvt_pk_bf16_f32 v74, v100, v101
	v_cvt_pk_bf16_f32 v75, v98, v99
	v_lshl_add_u64 v[64:65], v[166:167], 0, s[14:15]
	global_store_dwordx4 v[168:169], v[72:75], off nt
	v_pk_add_f32 v[102:103], v[70:71], v[104:105]
	v_pk_add_f32 v[104:105], v[68:69], v[130:131]
	v_mul_f32_e32 v89, v125, v125
	v_cvt_pk_bf16_f32 v68, v104, v105
	v_cvt_pk_bf16_f32 v69, v102, v103
	v_cvt_pk_bf16_f32 v70, v122, v123
	v_cvt_pk_bf16_f32 v71, v106, v107
	global_load_dwordx4 v[72:75], v[66:67], off nt
	global_load_dwordx4 v[76:79], v[64:65], off offset:256 nt
	v_mul_f32_e32 v90, v117, v117
	v_fmac_f32_e32 v89, v124, v124
	v_fmac_f32_e32 v90, v116, v116
	v_add_f32_e32 v89, v89, v90
	v_mul_f32_e32 v90, v119, v119
	v_mul_f32_e32 v91, v121, v121
	v_mul_f32_e32 v95, v95, v95
	v_mul_f32_e32 v93, v93, v93
	v_fmac_f32_e32 v90, v118, v118
	v_fmac_f32_e32 v91, v120, v120
	v_fmac_f32_e32 v95, v94, v94
	v_fmac_f32_e32 v93, v92, v92
	v_add_f32_e32 v90, v90, v91
	v_add_f32_e32 v92, v95, v93
	v_mul_f32_e32 v93, v101, v101
	v_mul_f32_e32 v94, v99, v99
	v_add_f32_e32 v89, v89, v90
	v_fmac_f32_e32 v93, v100, v100
	v_fmac_f32_e32 v94, v98, v98
	global_store_dwordx4 v[168:169], v[68:71], off offset:256 nt
	s_mov_b32 s14, 0x50000
	v_add_f32_e32 v97, v88, v89
	v_mul_f32_e32 v68, v105, v105
	s_waitcnt vmcnt(5)
	v_lshlrev_b32_e32 v118, 16, v114
	v_and_b32_e32 v119, 0xffff0000, v114
	v_lshlrev_b32_e32 v114, 16, v115
	v_and_b32_e32 v115, 0xffff0000, v115
	v_mul_f32_e32 v69, v103, v103
	v_lshlrev_b32_e32 v88, 16, v108
	v_and_b32_e32 v89, 0xffff0000, v108
	v_lshlrev_b32_e32 v90, 16, v109
	v_and_b32_e32 v91, 0xffff0000, v109
	v_lshlrev_b32_e32 v108, 16, v110
	v_and_b32_e32 v109, 0xffff0000, v110
	v_lshlrev_b32_e32 v110, 16, v111
	v_and_b32_e32 v111, 0xffff0000, v111
	v_add_f32_e32 v93, v93, v94
	v_fmac_f32_e32 v68, v104, v104
	v_fmac_f32_e32 v69, v102, v102
	v_pk_add_f32 v[94:95], v[50:51], v[114:115]
	v_add_co_u32_e32 v50, vcc, s14, v166
	v_lshlrev_b32_e32 v116, 16, v112
	v_and_b32_e32 v117, 0xffff0000, v112
	v_lshlrev_b32_e32 v112, 16, v113
	v_and_b32_e32 v113, 0xffff0000, v113
	v_add_f32_e32 v124, v68, v69
	v_pk_add_f32 v[62:63], v[62:63], v[90:91]
	v_pk_add_f32 v[60:61], v[60:61], v[88:89]
	v_pk_add_f32 v[58:59], v[58:59], v[110:111]
	v_pk_add_f32 v[56:57], v[56:57], v[108:109]
	v_cvt_pk_bf16_f32 v68, v60, v61
	v_cvt_pk_bf16_f32 v69, v62, v63
	v_addc_co_u32_e32 v51, vcc, 0, v167, vcc
	v_cvt_pk_bf16_f32 v70, v56, v57
	v_cvt_pk_bf16_f32 v71, v58, v59
	v_add_f32_e32 v121, v92, v93
	global_store_dwordx4 v[82:83], v[68:71], off nt
	v_pk_add_f32 v[82:83], v[54:55], v[112:113]
	v_pk_add_f32 v[92:93], v[52:53], v[116:117]
	v_pk_add_f32 v[98:99], v[48:49], v[118:119]
	v_cvt_pk_bf16_f32 v52, v92, v93
	v_cvt_pk_bf16_f32 v53, v82, v83
	s_mov_b64 s[14:15], 0x50000
	v_cvt_pk_bf16_f32 v54, v98, v99
	v_cvt_pk_bf16_f32 v55, v94, v95
	global_load_dwordx4 v[68:71], v[50:51], off nt
	v_lshl_add_u64 v[48:49], v[166:167], 0, s[14:15]
	global_load_dwordx4 v[88:91], v[48:49], off offset:256 nt
	s_mov_b32 s14, 0x58000
	v_mul_f32_e32 v108, v107, v107
	v_fmac_f32_e32 v108, v106, v106
	global_store_dwordx4 v[80:81], v[52:55], off offset:256 nt
	v_mul_f32_e32 v123, v123, v123
	v_fmac_f32_e32 v123, v122, v122
	ds_bpermute_b32 v86, v180, v84
	ds_bpermute_b32 v120, v180, v97
	s_waitcnt vmcnt(6)
; __device__ __forceinline__ unsigned cvt_pk_bf16(float lo, float hi) { unsigned r; asm volatile("v_cvt_pk_bf16_f32 %0, %1, %2" : "=v"(r) : "v"(lo), "v"(hi)); return r; }
; template <bool RD32>
; __device__ __forceinline__ void res_rows(const float* __restrict__ xold32, const bf16_t* __restrict__ xoldb, bf16_t* __restrict__ xb, float* __restrict__ ssq, const f32x4 (&acc)[2][2][4][2], int row0, int col0, int slot) {
;     ...
;     for (int idx = 0; idx < 8; ++idx) {
;         const int ai = idx >> 2, m = idx & 3; const int r = row0 + ai * HALF + m * 16; const size_t off = (size_t)r * D + col0;
;         if (idx < 7) { const int ai2 = (idx + 1) >> 2, m2 = (idx + 1) & 3; const size_t off2 = (size_t)(row0 + ai2 * HALF + m2 * 16) * D + col0;
; #pragma unroll
;             for (int bj = 0; bj < 2; ++bj) ld(off2 + bj * HALF, xo[(idx + 1) & 1][bj][0], xo[(idx + 1) & 1][bj][1]); }
;         float ss = 0.f;
; #pragma unroll
;         for (int bj = 0; bj < 2; ++bj) { const f32x4 x0 = xo[idx & 1][bj][0] + acc[ai][bj][m][0], x1 = xo[idx & 1][bj][1] + acc[ai][bj][m][1];
;             u32x4 w; w.x = cvt_pk_bf16(x0[0], x0[1]); w.y = cvt_pk_bf16(x0[2], x0[3]); w.z = cvt_pk_bf16(x1[0], x1[1]); w.w = cvt_pk_bf16(x1[2], x1[3]);
;             *(u32x4*)(xb + off + bj * HALF) = w;
;             ss += ((x0[0] * x0[0] + x0[1] * x0[1]) + (x0[2] * x0[2] + x0[3] * x0[3])) + ((x1[0] * x1[0] + x1[1] * x1[1]) + (x1[2] * x1[2] + x1[3] * x1[3])); }
;         ss += __shfl_xor(ss, 16); ss += __shfl_xor(ss, 32);
;         ssv[idx] = ss;
;     }
	v_lshlrev_b32_e32 v100, 16, v72
	s_waitcnt vmcnt(5)
	v_lshlrev_b32_e32 v104, 16, v76
	v_and_b32_e32 v105, 0xffff0000, v76
	v_and_b32_e32 v101, 0xffff0000, v72
	v_lshlrev_b32_e32 v72, 16, v73
	v_and_b32_e32 v73, 0xffff0000, v73
	v_lshlrev_b32_e32 v102, 16, v74
	v_and_b32_e32 v103, 0xffff0000, v74
	v_lshlrev_b32_e32 v74, 16, v75
	v_and_b32_e32 v75, 0xffff0000, v75
	v_pk_add_f32 v[36:37], v[36:37], v[104:105]
	v_add_co_u32_e32 v104, vcc, s14, v166
	v_lshlrev_b32_e32 v76, 16, v77
	v_and_b32_e32 v77, 0xffff0000, v77
	v_lshlrev_b32_e32 v106, 16, v78
	v_and_b32_e32 v107, 0xffff0000, v78
	v_lshlrev_b32_e32 v78, 16, v79
	v_and_b32_e32 v79, 0xffff0000, v79
	v_pk_add_f32 v[46:47], v[46:47], v[72:73]
	v_pk_add_f32 v[80:81], v[44:45], v[100:101]
	v_pk_add_f32 v[100:101], v[42:43], v[74:75]
	v_pk_add_f32 v[102:103], v[40:41], v[102:103]
	v_cvt_pk_bf16_f32 v40, v80, v81
	v_cvt_pk_bf16_f32 v41, v46, v47
	v_addc_co_u32_e32 v105, vcc, 0, v167, vcc
	v_cvt_pk_bf16_f32 v42, v102, v103
	v_cvt_pk_bf16_f32 v43, v100, v101
	global_store_dwordx4 v[66:67], v[40:43], off nt
	v_pk_add_f32 v[66:67], v[38:39], v[76:77]
	v_pk_add_f32 v[76:77], v[34:35], v[78:79]
	v_pk_add_f32 v[78:79], v[32:33], v[106:107]
	v_cvt_pk_bf16_f32 v42, v36, v37
	v_cvt_pk_bf16_f32 v43, v66, v67
	v_add_f32_e32 v32, v123, v108
	v_cvt_pk_bf16_f32 v44, v78, v79
	v_cvt_pk_bf16_f32 v45, v76, v77
	global_load_dwordx4 v[52:55], v[104:105], off nt
	v_add_f32_e32 v32, v124, v32
	s_mov_b64 s[14:15], 0x58000
	v_add_f32_e32 v34, v121, v32
	v_lshl_add_u64 v[32:33], v[166:167], 0, s[14:15]
	global_load_dwordx4 v[72:75], v[32:33], off offset:256 nt
	v_mul_f32_e32 v38, v61, v61
	v_mul_f32_e32 v39, v63, v63
	v_mul_f32_e32 v81, v81, v81
	v_mul_f32_e32 v47, v47, v47
	v_fmac_f32_e32 v38, v60, v60
	v_fmac_f32_e32 v39, v62, v62
	v_fmac_f32_e32 v81, v80, v80
	v_fmac_f32_e32 v47, v46, v46
	v_add_f32_e32 v38, v38, v39
	v_mul_f32_e32 v39, v57, v57
	v_mul_f32_e32 v40, v59, v59
	v_add_f32_e32 v46, v81, v47
	v_mul_f32_e32 v47, v103, v103
	v_mul_f32_e32 v80, v101, v101
	v_mul_f32_e32 v37, v37, v37
	v_fmac_f32_e32 v39, v56, v56
	v_fmac_f32_e32 v40, v58, v58
	v_fmac_f32_e32 v47, v102, v102
	v_fmac_f32_e32 v80, v100, v100
	v_fmac_f32_e32 v37, v36, v36
	v_mul_f32_e32 v36, v67, v67
	v_add_f32_e32 v47, v47, v80
	v_fmac_f32_e32 v36, v66, v66
	global_store_dwordx4 v[64:65], v[42:45], off offset:256 nt
	v_add_f32_e32 v46, v46, v47
	s_waitcnt vmcnt(6)
	v_lshlrev_b32_e32 v56, 16, v68
	v_and_b32_e32 v57, 0xffff0000, v68
	v_lshlrev_b32_e32 v58, 16, v69
	v_and_b32_e32 v59, 0xffff0000, v69
	v_lshlrev_b32_e32 v60, 16, v70
	v_and_b32_e32 v61, 0xffff0000, v70
	v_lshlrev_b32_e32 v62, 16, v71
	v_and_b32_e32 v63, 0xffff0000, v71
	v_pk_add_f32 v[30:31], v[30:31], v[58:59]
	v_pk_add_f32 v[28:29], v[28:29], v[56:57]
	v_pk_add_f32 v[58:59], v[24:25], v[60:61]
	v_cvt_pk_bf16_f32 v24, v28, v29
	v_cvt_pk_bf16_f32 v25, v30, v31
	v_add_f32_e32 v36, v37, v36
	v_mul_f32_e32 v37, v79, v79
	v_mul_f32_e32 v47, v77, v77
	v_pk_add_f32 v[56:57], v[26:27], v[62:63]
	v_cvt_pk_bf16_f32 v26, v58, v59
	v_fmac_f32_e32 v37, v78, v78
	v_cvt_pk_bf16_f32 v27, v56, v57
	global_store_dwordx4 v[50:51], v[24:27], off nt
	v_fmac_f32_e32 v47, v76, v76
	v_add_f32_e32 v37, v37, v47
	v_mul_f32_e32 v24, v29, v29
	v_mul_f32_e32 v25, v31, v31
	v_fmac_f32_e32 v24, v28, v28
	v_fmac_f32_e32 v25, v30, v30
	v_add_f32_e32 v24, v24, v25
	v_mul_f32_e32 v25, v59, v59
	v_mul_f32_e32 v26, v57, v57
	v_add_f32_e32 v39, v39, v40
	v_mul_f32_e32 v40, v83, v83
	s_waitcnt vmcnt(6)
	v_lshlrev_b32_e32 v68, 16, v88
	v_and_b32_e32 v69, 0xffff0000, v88
	v_add_f32_e32 v36, v36, v37
	v_fmac_f32_e32 v25, v58, v58
	v_fmac_f32_e32 v26, v56, v56
	v_fmac_f32_e32 v40, v82, v82
	v_lshlrev_b32_e32 v70, 16, v89
	v_and_b32_e32 v71, 0xffff0000, v89
	v_lshlrev_b32_e32 v82, 16, v90
	v_add_f32_e32 v36, v46, v36
	v_and_b32_e32 v83, 0xffff0000, v90
	v_lshlrev_b32_e32 v46, 16, v91
	v_and_b32_e32 v47, 0xffff0000, v91
	v_add_f32_e32 v25, v25, v26
	v_pk_add_f32 v[20:21], v[20:21], v[68:69]
	v_add_f32_e32 v26, v24, v25
	v_pk_add_f32 v[22:23], v[22:23], v[70:71]
	v_pk_add_f32 v[24:25], v[18:19], v[46:47]
	v_pk_add_f32 v[18:19], v[16:17], v[82:83]
	v_mul_f32_e32 v17, v21, v21
	v_cvt_pk_bf16_f32 v16, v20, v21
	v_fmac_f32_e32 v17, v20, v20
	v_mul_f32_e32 v20, v23, v23
	v_fmac_f32_e32 v20, v22, v22
	v_add_f32_e32 v17, v17, v20
	v_mul_f32_e32 v20, v19, v19
	v_mul_f32_e32 v21, v25, v25
	v_fmac_f32_e32 v20, v18, v18
	v_fmac_f32_e32 v21, v24, v24
	v_add_f32_e32 v20, v20, v21
	v_add_f32_e32 v17, v17, v20
	v_add_f32_e32 v20, v26, v17
	ds_bpermute_b32 v21, v180, v20
	s_waitcnt vmcnt(3)
; __device__ __forceinline__ unsigned cvt_pk_bf16(float lo, float hi) { unsigned r; asm volatile("v_cvt_pk_bf16_f32 %0, %1, %2" : "=v"(r) : "v"(lo), "v"(hi)); return r; }
; template <bool RD32>
; __device__ __forceinline__ void res_rows(const float* __restrict__ xold32, const bf16_t* __restrict__ xoldb, bf16_t* __restrict__ xb, float* __restrict__ ssq, const f32x4 (&acc)[2][2][4][2], int row0, int col0, int slot) {
;     ...
;     for (int idx = 0; idx < 8; ++idx) {
;         const int ai = idx >> 2, m = idx & 3; const int r = row0 + ai * HALF + m * 16; const size_t off = (size_t)r * D + col0;
;         if (idx < 7) { const int ai2 = (idx + 1) >> 2, m2 = (idx + 1) & 3; const size_t off2 = (size_t)(row0 + ai2 * HALF + m2 * 16) * D + col0;
; #pragma unroll
;             for (int bj = 0; bj < 2; ++bj) ld(off2 + bj * HALF, xo[(idx + 1) & 1][bj][0], xo[(idx + 1) & 1][bj][1]); }
;         float ss = 0.f;
; #pragma unroll
;         for (int bj = 0; bj < 2; ++bj) { const f32x4 x0 = xo[idx & 1][bj][0] + acc[ai][bj][m][0], x1 = xo[idx & 1][bj][1] + acc[ai][bj][m][1];
;             u32x4 w; w.x = cvt_pk_bf16(x0[0], x0[1]); w.y = cvt_pk_bf16(x0[2], x0[3]); w.z = cvt_pk_bf16(x1[0], x1[1]); w.w = cvt_pk_bf16(x1[2], x1[3]);
;             *(u32x4*)(xb + off + bj * HALF) = w;
;             ss += ((x0[0] * x0[0] + x0[1] * x0[1]) + (x0[2] * x0[2] + x0[3] * x0[3])) + ((x1[0] * x1[0] + x1[1] * x1[1]) + (x1[2] * x1[2] + x1[3] * x1[3])); }
;         ss += __shfl_xor(ss, 16); ss += __shfl_xor(ss, 32);
;         ssv[idx] = ss;
;     }
;     const int fq = slot >> 6;
; #pragma unroll
;     for (int j = 0; j < 2; ++j) { const float v = fq == 0 ? ssv[j] : fq == 1 ? ssv[2 + j] : fq == 2 ? ssv[4 + j] : ssv[6 + j]; const int idx = 2 * fq + j;
;         ssq[(size_t)(row0 + (idx >> 2) * HALF + (idx & 3) * 16) * 16 + (slot & 15)] = v; }
	v_lshlrev_b32_e32 v42, 16, v52
	v_and_b32_e32 v43, 0xffff0000, v52
	v_lshlrev_b32_e32 v44, 16, v53
	v_and_b32_e32 v45, 0xffff0000, v53
	v_lshlrev_b32_e32 v52, 16, v54
	v_and_b32_e32 v53, 0xffff0000, v54
	v_lshlrev_b32_e32 v54, 16, v55
	v_and_b32_e32 v55, 0xffff0000, v55
	v_cvt_pk_bf16_f32 v17, v22, v23
	v_cvt_pk_bf16_f32 v18, v18, v19
	v_cvt_pk_bf16_f32 v19, v24, v25
	global_store_dwordx4 v[48:49], v[16:19], off offset:256 nt
	v_pk_add_f32 v[14:15], v[14:15], v[44:45]
	v_pk_add_f32 v[12:13], v[12:13], v[42:43]
	s_waitcnt lgkmcnt(0)
	v_add_f32_e32 v16, v20, v21
	v_pk_add_f32 v[20:21], v[8:9], v[52:53]
	v_cvt_pk_bf16_f32 v8, v12, v13
	v_cvt_pk_bf16_f32 v9, v14, v15
	v_pk_add_f32 v[18:19], v[10:11], v[54:55]
	v_cvt_pk_bf16_f32 v10, v20, v21
	s_waitcnt vmcnt(3)
	v_lshlrev_b32_e32 v64, 16, v72
	v_cvt_pk_bf16_f32 v11, v18, v19
	global_store_dwordx4 v[104:105], v[8:11], off nt
	v_and_b32_e32 v65, 0xffff0000, v72
	v_lshlrev_b32_e32 v66, 16, v73
	v_mul_f32_e32 v8, v13, v13
	v_mul_f32_e32 v9, v15, v15
	v_fmac_f32_e32 v8, v12, v12
	v_fmac_f32_e32 v9, v14, v14
	v_add_f32_e32 v8, v8, v9
	v_mul_f32_e32 v9, v21, v21
	v_mul_f32_e32 v10, v19, v19
	v_fmac_f32_e32 v9, v20, v20
	v_fmac_f32_e32 v10, v18, v18
	v_and_b32_e32 v67, 0xffff0000, v73
	v_lshlrev_b32_e32 v72, 16, v74
	v_and_b32_e32 v73, 0xffff0000, v74
	v_lshlrev_b32_e32 v74, 16, v75
	v_and_b32_e32 v75, 0xffff0000, v75
	v_add_f32_e32 v9, v9, v10
	v_pk_add_f32 v[4:5], v[4:5], v[64:65]
	v_add_f32_e32 v10, v8, v9
	v_pk_add_f32 v[6:7], v[6:7], v[66:67]
	v_pk_add_f32 v[8:9], v[2:3], v[74:75]
	v_pk_add_f32 v[2:3], v[0:1], v[72:73]
	v_mul_f32_e32 v1, v5, v5
	v_add_f32_e32 v38, v38, v39
	v_mul_f32_e32 v39, v93, v93
	v_cvt_pk_bf16_f32 v0, v4, v5
	v_fmac_f32_e32 v1, v4, v4
	v_mul_f32_e32 v4, v7, v7
	v_fmac_f32_e32 v39, v92, v92
	v_fmac_f32_e32 v4, v6, v6
	v_add_f32_e32 v39, v39, v40
	v_mul_f32_e32 v40, v99, v99
	v_mul_f32_e32 v41, v95, v95
	v_add_f32_e32 v1, v1, v4
	v_mul_f32_e32 v4, v3, v3
	v_mul_f32_e32 v5, v9, v9
	v_fmac_f32_e32 v40, v98, v98
	v_fmac_f32_e32 v41, v94, v94
	v_fmac_f32_e32 v4, v2, v2
	v_fmac_f32_e32 v5, v8, v8
	v_add_f32_e32 v40, v40, v41
	v_add_f32_e32 v4, v4, v5
	v_add_f32_e32 v39, v39, v40
	v_add_f32_e32 v1, v1, v4
	v_add_f32_e32 v40, v38, v39
	v_add_f32_e32 v4, v10, v1
	ds_bpermute_b32 v35, v180, v34
	ds_bpermute_b32 v41, v180, v40
	ds_bpermute_b32 v37, v180, v36
	ds_bpermute_b32 v5, v180, v4
	v_cvt_pk_bf16_f32 v1, v6, v7
	v_cvt_pk_bf16_f32 v2, v2, v3
	v_lshlrev_b32_e32 v87, 2, v85
	v_add_f32_e32 v84, v84, v86
	v_add_f32_e32 v38, v97, v120
	s_waitcnt lgkmcnt(3)
	v_add_f32_e32 v34, v34, v35
	s_waitcnt lgkmcnt(2)
	v_add_f32_e32 v40, v40, v41
	s_waitcnt lgkmcnt(1)
	v_add_f32_e32 v36, v36, v37
	v_cvt_pk_bf16_f32 v3, v8, v9
	global_store_dwordx4 v[32:33], v[0:3], off offset:256 nt
	ds_bpermute_b32 v85, v87, v96
	ds_bpermute_b32 v86, v87, v84
	s_waitcnt lgkmcnt(2)
	v_add_f32_e32 v2, v4, v5
	ds_bpermute_b32 v39, v87, v38
	ds_bpermute_b32 v35, v87, v34
	ds_bpermute_b32 v41, v87, v40
	ds_bpermute_b32 v37, v87, v36
	ds_bpermute_b32 v17, v87, v16
	ds_bpermute_b32 v3, v87, v2
	s_and_b32 s14, s29, 12
	s_or_b32 s14, s14, s11
	s_lshl_b32 s14, s14, 2
	v_bitop3_b32 v0, s29, v216, v177 bitop3:0xc8
	s_add_u32 s46, s18, s14
	v_cmp_lt_u32_e32 vcc, 63, v179
	v_add_u32_e32 v0, v164, v0
	s_addc_u32 s47, s19, 0
	s_and_saveexec_b64 s[14:15], vcc
	s_xor_b64 s[48:49], exec, s[14:15]
	s_cbranch_execz .LBB0_626
	v_ashrrev_i32_e32 v4, 6, v179
	v_cmp_lt_i32_e32 vcc, 1, v4
	s_mov_b64 s[42:43], 0
	s_and_saveexec_b64 s[14:15], vcc
	s_xor_b64 s[50:51], exec, s[14:15]
	s_cbranch_execnz .LBB0_631
	s_or_saveexec_b64 s[50:51], s[50:51]
	v_cmp_ne_u32_e32 vcc, 1, v4
	s_xor_b64 exec, exec, s[50:51]
	s_cbranch_execnz .LBB0_634

; __device__ __forceinline__ float bflo(unsigned w) { return __uint_as_float(w << 16); }
; __device__ __forceinline__ float bfhi(unsigned w) { return __uint_as_float(w & 0xffff0000u); }
; __global__ void __launch_bounds__(512, 2) fwd_megakernel(Params p) {
;     ...
;     { const int tid = threadIdx.x;
;       for (size_t i = ((size_t)bx * 512 + tid) * 8; i < (size_t)T * D; i += (size_t)G * 512 * 8) {
;           const int r = (int)(i >> 10), c = (int)(i & 1023);
;           const float* sp = SSQ + (size_t)r * 16; float s = 0.f;
; #pragma unroll
;           for (int j = 0; j < 4; ++j) { const f32x4 q = *(const f32x4*)(sp + 4 * j); s += (q[0] + q[1]) + (q[2] + q[3]); }
;           const float rs = rsqrtf(s * (1.0f / 1024.0f) + EPS);
;           const u32x4 w = *(const u32x4*)(XB + i); const f32x4 g0 = *(const f32x4*)(p.final_norm_g + c), g1 = *(const f32x4*)(p.final_norm_g + c + 4);
;           *(f32x4*)(p.out + i) = (f32x4){bflo(w.x), bfhi(w.x), bflo(w.y), bfhi(w.y)} * rs * g0;
;           *(f32x4*)(p.out + i + 4) = (f32x4){bflo(w.z), bfhi(w.z), bflo(w.w), bfhi(w.w)} * rs * g1; } }
.LBB0_692:
	v_lshrrev_b32_e32 v7, 4, v0
	v_and_b32_e32 v7, 0x3fffc0, v7
	global_load_dwordx4 v[8:11], v7, s[12:13] offset:48
	global_load_dwordx4 v[12:15], v7, s[12:13] offset:32
	global_load_dwordx4 v[16:19], v7, s[12:13] offset:16
	global_load_dwordx4 v[20:23], v7, s[12:13]
	global_load_dwordx4 v[24:27], v[2:3], off nt
	v_and_b32_e32 v7, 0x3f8, v0
	v_lshlrev_b32_e32 v7, 2, v7
	global_load_dwordx4 v[28:31], v7, s[14:15]
	global_load_dwordx4 v[32:35], v7, s[14:15] offset:16
	v_lshl_add_u64 v[0:1], v[0:1], 0, s[0:1]
	v_cmp_lt_u64_e32 vcc, s[8:9], v[0:1]
	s_or_b64 s[6:7], vcc, s[6:7]
	v_lshl_add_u64 v[2:3], v[2:3], 0, s[4:5]
	s_waitcnt vmcnt(5)
	v_add_f32_e32 v12, v12, v13
	v_add_f32_e32 v14, v14, v15
	s_waitcnt vmcnt(3)
	v_mov_b32_e32 v40, v21
	v_mov_b32_e32 v41, v22
	v_mov_b32_e32 v21, v23
	v_mov_b32_e32 v22, v17
	v_mov_b32_e32 v23, v18
	v_mov_b32_e32 v17, v19
	v_mov_b32_e32 v13, v10
	v_mov_b32_e32 v15, v11
	v_pk_add_f32 v[10:11], v[40:41], v[20:21]
	v_pk_add_f32 v[16:17], v[22:23], v[16:17]
	v_add_f32_e32 v7, v10, v11
	v_pk_add_f32 v[10:11], v[16:17], v[16:17] op_sel:[0,1] op_sel_hi:[1,0]
	v_mov_b32_e32 v19, v8
	v_add_f32_e32 v18, 0, v7
	v_mov_b32_e32 v11, v9
	v_pk_add_f32 v[12:13], v[12:13], v[14:15]
	v_pk_add_f32 v[8:9], v[18:19], v[10:11]
	s_waitcnt vmcnt(2)
	v_lshlrev_b32_e32 v36, 16, v24
	v_pk_add_f32 v[8:9], v[8:9], v[12:13]
	v_and_b32_e32 v37, 0xffff0000, v24
	v_add_f32_e32 v7, v8, v9
	v_fmamk_f32 v7, v7, 0x3a800000, v6
	v_mul_f32_e32 v8, 0x4b800000, v7
	v_cmp_gt_f32_e32 vcc, s10, v7
	v_lshlrev_b32_e32 v24, 16, v25
	v_and_b32_e32 v25, 0xffff0000, v25
	v_cndmask_b32_e32 v7, v7, v8, vcc
	v_rsq_f32_e32 v7, v7
	v_lshlrev_b32_e32 v38, 16, v26
	v_and_b32_e32 v39, 0xffff0000, v26
	v_lshlrev_b32_e32 v26, 16, v27
	v_mul_f32_e32 v8, 0x45800000, v7
	v_cndmask_b32_e32 v8, v7, v8, vcc
	v_and_b32_e32 v27, 0xffff0000, v27
	v_pk_mul_f32 v[12:13], v[8:9], v[36:37] op_sel_hi:[0,1]
	v_pk_mul_f32 v[10:11], v[8:9], v[24:25] op_sel_hi:[0,1]
	v_pk_mul_f32 v[16:17], v[8:9], v[38:39] op_sel_hi:[0,1]
	v_pk_mul_f32 v[14:15], v[8:9], v[26:27] op_sel_hi:[0,1]
	s_waitcnt vmcnt(1)
	v_pk_mul_f32 v[10:11], v[30:31], v[10:11]
	v_pk_mul_f32 v[8:9], v[28:29], v[12:13]
	s_waitcnt vmcnt(0)
	v_pk_mul_f32 v[14:15], v[34:35], v[14:15]
	v_pk_mul_f32 v[12:13], v[32:33], v[16:17]
	global_store_dwordx4 v[4:5], v[8:11], off offset:-16 nt
	global_store_dwordx4 v[4:5], v[12:15], off nt
	v_lshl_add_u64 v[4:5], v[4:5], 0, s[2:3]
	s_andn2_b64 exec, exec, s[6:7]
	s_cbranch_execnz .LBB0_692
